# FFT stage-A 16-bit LDS gathers batched eight pairs per wait instead of one pair per wait
# baseline (speedup 1.0000x reference)
; #define LAS __attribute__((address_space(3)))
; #define GAS __attribute__((address_space(1)))
; __device__ __forceinline__ void fft_phase(const Params& p, LAS unsigned char* lds, int tid) {
;     ...
;         const int b = u >> 5, g = (u >> 3) & 3, cb = u & 7;
;         {
;             u32x4 v[16];
; #pragma unroll
;             for (int j = 0; j < 16; ++j) v[j] = *(const u32x4*)(ZT + ((size_t)((j >> 3) * 2048 + b * 256 + g * 64 + cb * 8 + (j & 7))) * 4096 + tid * 8);
; #pragma unroll
;             for (int j = 0; j < 16; ++j) *(LAS u32x4*)(Z + j * 4096 + tid * 8) = v[j];
;         }
;         __syncthreads();
;         LAS unsigned short* Zr = Z + w * 4096; LAS unsigned short* Zi = Z + (8 + w) * 4096;
;         for (int nh = 0; nh < 2; ++nh) {
;             const int n2 = nh * 32 + r32;
;             int two = (n2 * 64 + 4 * hi) * 2; asm volatile("" : "+v"(two));
;             const GAS float* twp = (const GAS float*)TW + two;
;             f32x4 tw0[2][4], tw1[2][4];
; #pragma unroll
;             for (int rg = 0; rg < 4; ++rg) { tw0[0][rg] = *(const GAS f32x4*)(twp + (8 * rg) * 2); tw1[0][rg] = *(const GAS f32x4*)(twp + (8 * rg) * 2 + 4); }
;             bf16x8 bfA[8];
; #pragma unroll
;             for (int s = 0; s < 8; ++s) {
;                 const LAS unsigned short* q = Z + ((s >> 2) * 8 + w) * 4096 + (16 * (s & 3) + 8 * hi) * 64 + n2;
;                 u32x4 t;
;                 t.x = (unsigned)q[0] | ((unsigned)q[64] << 16); t.y = (unsigned)q[128] | ((unsigned)q[192] << 16);
;                 t.z = (unsigned)q[256] | ((unsigned)q[320] << 16); t.w = (unsigned)q[384] | ((unsigned)q[448] << 16);
;                 bfA[s] = __builtin_bit_cast(bf16x8, t);
;             }
.LBB0_454:
	s_ashr_i32 s6, s5, 5
	s_and_b32 s7, s4, 0xf8
	s_lshl_b32 s8, s6, 8
	s_or_b32 s8, s8, s7
	s_ashr_i32 s9, s8, 31
	s_lshl_b64 s[10:11], s[8:9], 13
	v_lshl_add_u64 v[0:1], v[124:125], 0, s[10:11]
	s_or_b32 s10, s8, 1
	s_ashr_i32 s11, s10, 31
	s_lshl_b64 s[10:11], s[10:11], 13
	v_lshl_add_u64 v[4:5], v[124:125], 0, s[10:11]
	s_or_b32 s10, s8, 2
	s_ashr_i32 s11, s10, 31
	s_lshl_b64 s[10:11], s[10:11], 13
	v_lshl_add_u64 v[8:9], v[124:125], 0, s[10:11]
	s_or_b32 s10, s8, 3
	s_ashr_i32 s11, s10, 31
	s_lshl_b64 s[10:11], s[10:11], 13
	v_lshl_add_u64 v[12:13], v[124:125], 0, s[10:11]
	s_or_b32 s10, s8, 4
	s_ashr_i32 s11, s10, 31
	s_lshl_b64 s[10:11], s[10:11], 13
	v_lshl_add_u64 v[16:17], v[124:125], 0, s[10:11]
	s_or_b32 s10, s8, 5
	s_ashr_i32 s11, s10, 31
	s_lshl_b64 s[10:11], s[10:11], 13
	v_lshl_add_u64 v[20:21], v[124:125], 0, s[10:11]
	s_or_b32 s10, s8, 6
	s_ashr_i32 s11, s10, 31
	s_lshl_b64 s[10:11], s[10:11], 13
	v_lshl_add_u64 v[24:25], v[124:125], 0, s[10:11]
	s_or_b32 s10, s8, 7
	s_ashr_i32 s11, s10, 31
	s_lshl_b64 s[10:11], s[10:11], 13
	v_lshl_add_u64 v[28:29], v[124:125], 0, s[10:11]
	s_add_i32 s10, s8, 0x800
	s_ashr_i32 s11, s10, 31
	s_lshl_b64 s[10:11], s[10:11], 13
	v_lshl_add_u64 v[32:33], v[124:125], 0, s[10:11]
	s_add_i32 s10, s8, 0x801
	s_ashr_i32 s11, s10, 31
	s_lshl_b64 s[10:11], s[10:11], 13
	v_lshl_add_u64 v[36:37], v[124:125], 0, s[10:11]
	s_add_i32 s10, s8, 0x802
	s_ashr_i32 s11, s10, 31
	s_lshl_b64 s[10:11], s[10:11], 13
	v_lshl_add_u64 v[40:41], v[124:125], 0, s[10:11]
	s_add_i32 s10, s8, 0x803
	s_ashr_i32 s11, s10, 31
	s_lshl_b64 s[10:11], s[10:11], 13
	v_lshl_add_u64 v[44:45], v[124:125], 0, s[10:11]
	s_add_i32 s10, s8, 0x804
	s_ashr_i32 s11, s10, 31
	s_lshl_b64 s[10:11], s[10:11], 13
	global_load_dwordx4 v[0:3], v[0:1], off
	v_lshl_add_u64 v[48:49], v[124:125], 0, s[10:11]
	s_add_i32 s10, s8, 0x805
	global_load_dwordx4 v[4:7], v[4:5], off
	s_ashr_i32 s11, s10, 31
	global_load_dwordx4 v[32:35], v[32:33], off
	s_lshl_b64 s[10:11], s[10:11], 13
	global_load_dwordx4 v[8:11], v[8:9], off
	v_lshl_add_u64 v[52:53], v[124:125], 0, s[10:11]
	global_load_dwordx4 v[36:39], v[36:37], off
	s_add_i32 s10, s8, 0x806
	global_load_dwordx4 v[12:15], v[12:13], off
	s_ashr_i32 s11, s10, 31
	global_load_dwordx4 v[40:43], v[40:41], off
	s_addk_i32 s8, 0x807
	global_load_dwordx4 v[16:19], v[16:17], off
	s_lshl_b64 s[10:11], s[10:11], 13
	global_load_dwordx4 v[44:47], v[44:45], off
	s_ashr_i32 s9, s8, 31
	global_load_dwordx4 v[20:23], v[20:21], off
	v_lshl_add_u64 v[56:57], v[124:125], 0, s[10:11]
	global_load_dwordx4 v[48:51], v[48:49], off
	s_lshl_b64 s[8:9], s[8:9], 13
	global_load_dwordx4 v[24:27], v[24:25], off
	v_lshl_add_u64 v[60:61], v[124:125], 0, s[8:9]
	global_load_dwordx4 v[52:55], v[52:53], off
	s_and_b32 s0, s4, 56
	global_load_dwordx4 v[28:31], v[28:29], off
	s_lshl_b32 s6, s6, 12
	global_load_dwordx4 v[56:59], v[56:57], off
	s_and_b32 s1, s4, 0xc0
	global_load_dwordx4 v[60:63], v[60:61], off
	s_lshl_b32 s76, s1, 1
	s_mov_b32 s1, s77
	s_add_i32 s5, s5, s90
	s_add_i32 s4, s4, s40
	s_waitcnt vmcnt(15)
	ds_write_b128 v128, v[0:3]
	s_waitcnt vmcnt(14)
	ds_write_b128 v128, v[4:7] offset:8192
	s_waitcnt vmcnt(12)
	ds_write_b128 v128, v[8:11] offset:16384
	s_waitcnt vmcnt(10)
	ds_write_b128 v128, v[12:15] offset:24576
	s_waitcnt vmcnt(8)
	ds_write_b128 v128, v[16:19] offset:32768
	s_waitcnt vmcnt(6)
	ds_write_b128 v128, v[20:23] offset:40960
	s_waitcnt vmcnt(4)
	ds_write_b128 v128, v[24:27] offset:49152
	s_waitcnt vmcnt(2)
	ds_write_b128 v128, v[28:31] offset:57344
	v_add_u32_e32 v0, 0x10000, v128
	ds_write_b128 v0, v[32:35]
	v_add_u32_e32 v0, 0x12000, v128
	ds_write_b128 v0, v[36:39]
	v_add_u32_e32 v0, 0x14000, v128
	ds_write_b128 v0, v[40:43]
	v_add_u32_e32 v0, 0x16000, v128
	ds_write_b128 v0, v[44:47]
	v_add_u32_e32 v0, 0x18000, v128
	ds_write_b128 v0, v[48:51]
	v_add_u32_e32 v0, 0x1a000, v128
	ds_write_b128 v0, v[52:55]
	v_add_u32_e32 v0, 0x1c000, v128
	s_waitcnt vmcnt(1)
	ds_write_b128 v0, v[56:59]
	v_add_u32_e32 v0, 0x1e000, v128
	s_waitcnt vmcnt(0)
	ds_write_b128 v0, v[60:63]
	v_mov_b32_e32 v0, v129
	s_waitcnt lgkmcnt(0)
	s_barrier
	s_nop 0
	v_ashrrev_i32_e32 v1, 31, v0
	v_lshl_add_u64 v[126:127], v[0:1], 2, s[12:13]
	global_load_dwordx4 v[88:91], v[126:127], off offset:16
	global_load_dwordx4 v[92:95], v[126:127], off
	global_load_dwordx4 v[80:83], v[126:127], off offset:80
	global_load_dwordx4 v[84:87], v[126:127], off offset:64
	global_load_dwordx4 v[72:75], v[126:127], off offset:144
	global_load_dwordx4 v[76:79], v[126:127], off offset:128
	global_load_dwordx4 v[64:67], v[126:127], off offset:208
	global_load_dwordx4 v[68:71], v[126:127], off offset:192
	ds_read_u16 v0, v130
	ds_read_u16 v1, v130 offset:128
	ds_read_u16 v2, v130 offset:256
	ds_read_u16 v3, v130 offset:384
	ds_read_u16 v4, v130 offset:512
	ds_read_u16 v5, v130 offset:640
	ds_read_u16 v6, v130 offset:768
	ds_read_u16 v7, v130 offset:896
	ds_read_u16 v8, v130 offset:2048
	ds_read_u16 v9, v130 offset:2176
	ds_read_u16 v10, v130 offset:2304
	ds_read_u16 v11, v130 offset:2432
	ds_read_u16 v12, v130 offset:2560
	ds_read_u16 v13, v130 offset:2688
	ds_read_u16 v14, v130 offset:2816
	ds_read_u16 v15, v130 offset:2944
	s_waitcnt lgkmcnt(0)
	v_lshl_or_b32 v32, v1, 16, v0
	v_lshl_or_b32 v33, v3, 16, v2
	v_lshl_or_b32 v34, v5, 16, v4
	v_lshl_or_b32 v35, v7, 16, v6
	v_lshl_or_b32 v120, v9, 16, v8
	v_lshl_or_b32 v121, v11, 16, v10
	v_lshl_or_b32 v122, v13, 16, v12
	v_lshl_or_b32 v123, v15, 16, v14
	ds_read_u16 v0, v130 offset:4096
	ds_read_u16 v1, v130 offset:4224
	ds_read_u16 v2, v130 offset:4352
	ds_read_u16 v3, v130 offset:4480
	ds_read_u16 v4, v130 offset:4608
	ds_read_u16 v5, v130 offset:4736
	ds_read_u16 v6, v130 offset:4864
	ds_read_u16 v7, v130 offset:4992
	ds_read_u16 v8, v130 offset:6144
	ds_read_u16 v9, v130 offset:6272
	ds_read_u16 v10, v130 offset:6400
	ds_read_u16 v11, v130 offset:6528
	ds_read_u16 v12, v130 offset:6656
	ds_read_u16 v13, v130 offset:6784
	ds_read_u16 v14, v130 offset:6912
	ds_read_u16 v15, v130 offset:7040
	s_waitcnt lgkmcnt(0)
; #define LAS __attribute__((address_space(3)))
; #define GAS __attribute__((address_space(1)))
; __device__ __forceinline__ void fft_phase(const Params& p, LAS unsigned char* lds, int tid) {
;     ...
;             bf16x8 bfA[8];
; #pragma unroll
;             for (int s = 0; s < 8; ++s) {
;                 const LAS unsigned short* q = Z + ((s >> 2) * 8 + w) * 4096 + (16 * (s & 3) + 8 * hi) * 64 + n2;
;                 u32x4 t;
;                 t.x = (unsigned)q[0] | ((unsigned)q[64] << 16); t.y = (unsigned)q[128] | ((unsigned)q[192] << 16);
;                 t.z = (unsigned)q[256] | ((unsigned)q[320] << 16); t.w = (unsigned)q[384] | ((unsigned)q[448] << 16);
;                 bfA[s] = __builtin_bit_cast(bf16x8, t);
;             }
;             f32x16 acc[4];
;             int fao = r32 * 128 + 8 * hi; asm volatile("" : "+v"(fao));
;             const GAS bf16_t* fap = (const GAS bf16_t*)FA + fao;
; #pragma unroll
;             for (int mt = 0; mt < 4; ++mt) {
; #pragma unroll
;                 for (int e = 0; e < 16; ++e) acc[mt][e] = 0.f;
; #pragma unroll
;                 for (int s = 0; s < 8; ++s) {
;                     const bf16x8 a = *(const GAS bf16x8*)(fap + mt * 32 * 128 + 16 * s);
;                     acc[mt] = __builtin_amdgcn_mfma_f32_32x32x16_bf16(a, bfA[s], acc[mt], 0, 0, 0);
;                 }
;                 asm volatile("" ::: "memory");
;             }
	v_lshl_or_b32 v116, v1, 16, v0
	v_lshl_or_b32 v117, v3, 16, v2
	v_lshl_or_b32 v118, v5, 16, v4
	v_lshl_or_b32 v119, v7, 16, v6
	v_lshl_or_b32 v112, v9, 16, v8
	v_lshl_or_b32 v113, v11, 16, v10
	v_lshl_or_b32 v114, v13, 16, v12
	v_lshl_or_b32 v115, v15, 16, v14
	ds_read_u16 v0, v131
	ds_read_u16 v1, v131 offset:128
	ds_read_u16 v2, v131 offset:256
	ds_read_u16 v3, v131 offset:384
	ds_read_u16 v4, v131 offset:512
	ds_read_u16 v5, v131 offset:640
	ds_read_u16 v6, v131 offset:768
	ds_read_u16 v7, v131 offset:896
	ds_read_u16 v8, v131 offset:2048
	ds_read_u16 v9, v131 offset:2176
	ds_read_u16 v10, v131 offset:2304
	ds_read_u16 v11, v131 offset:2432
	ds_read_u16 v12, v131 offset:2560
	ds_read_u16 v13, v131 offset:2688
	ds_read_u16 v14, v131 offset:2816
	ds_read_u16 v15, v131 offset:2944
	s_waitcnt lgkmcnt(0)
	v_lshl_or_b32 v108, v1, 16, v0
	v_lshl_or_b32 v109, v3, 16, v2
	v_lshl_or_b32 v110, v5, 16, v4
	v_lshl_or_b32 v111, v7, 16, v6
	v_lshl_or_b32 v104, v9, 16, v8
	v_lshl_or_b32 v105, v11, 16, v10
	v_lshl_or_b32 v106, v13, 16, v12
	v_lshl_or_b32 v107, v15, 16, v14
	ds_read_u16 v0, v131 offset:4096
	ds_read_u16 v1, v131 offset:4224
	ds_read_u16 v2, v131 offset:4352
	ds_read_u16 v3, v131 offset:4480
	ds_read_u16 v4, v131 offset:4608
	ds_read_u16 v5, v131 offset:4736
	ds_read_u16 v6, v131 offset:4864
	ds_read_u16 v7, v131 offset:4992
	ds_read_u16 v8, v131 offset:6144
	ds_read_u16 v9, v131 offset:6272
	ds_read_u16 v10, v131 offset:6400
	ds_read_u16 v11, v131 offset:6528
	ds_read_u16 v12, v131 offset:6656
	ds_read_u16 v13, v131 offset:6784
	ds_read_u16 v14, v131 offset:6912
	ds_read_u16 v15, v131 offset:7040
	s_waitcnt lgkmcnt(0)
	v_lshl_or_b32 v96, v1, 16, v0
	v_lshl_or_b32 v97, v3, 16, v2
	v_lshl_or_b32 v98, v5, 16, v4
	v_lshl_or_b32 v99, v7, 16, v6
	v_lshl_or_b32 v100, v9, 16, v8
	v_lshl_or_b32 v101, v11, 16, v10
	v_lshl_or_b32 v102, v13, 16, v12
	v_lshl_or_b32 v103, v15, 16, v14
	v_mov_b32_e32 v0, v129
	s_nop 0
	v_ashrrev_i32_e32 v1, 31, v0
	v_lshl_add_u64 v[36:37], v[0:1], 1, s[28:29]
	global_load_dwordx4 v[0:3], v[36:37], off
	v_add_co_u32_e32 v42, vcc, s19, v36
	s_waitcnt vmcnt(0)
	v_mfma_f32_32x32x16_bf16 v[16:31], v[0:3], v[32:35], 0
	global_load_dwordx4 v[0:3], v[36:37], off offset:32
	v_addc_co_u32_e32 v43, vcc, 0, v37, vcc
	s_waitcnt vmcnt(0)
	v_mfma_f32_32x32x16_bf16 v[16:31], v[0:3], v[120:123], v[16:31]
	global_load_dwordx4 v[0:3], v[36:37], off offset:64
	s_waitcnt vmcnt(0)
	v_mfma_f32_32x32x16_bf16 v[16:31], v[0:3], v[116:119], v[16:31]
	global_load_dwordx4 v[0:3], v[36:37], off offset:96
	s_waitcnt vmcnt(0)
	v_mfma_f32_32x32x16_bf16 v[16:31], v[0:3], v[112:115], v[16:31]
	global_load_dwordx4 v[0:3], v[36:37], off offset:128
	s_waitcnt vmcnt(0)
	v_mfma_f32_32x32x16_bf16 v[16:31], v[0:3], v[108:111], v[16:31]
	global_load_dwordx4 v[0:3], v[36:37], off offset:160
	s_waitcnt vmcnt(0)
	v_mfma_f32_32x32x16_bf16 v[16:31], v[0:3], v[104:107], v[16:31]
	global_load_dwordx4 v[0:3], v[36:37], off offset:192
	s_waitcnt vmcnt(0)
	v_mfma_f32_32x32x16_bf16 v[16:31], v[0:3], v[96:99], v[16:31]
	global_load_dwordx4 v[0:3], v[36:37], off offset:224
	global_load_dwordx4 v[38:41], v[42:43], off offset:32
	s_waitcnt vmcnt(1)
	v_mfma_f32_32x32x16_bf16 v[16:31], v[0:3], v[100:103], v[16:31]
	global_load_dwordx4 v[0:3], v[42:43], off
	s_waitcnt vmcnt(0)
	v_mfma_f32_32x32x16_bf16 v[0:15], v[0:3], v[32:35], 0
	v_mfma_f32_32x32x16_bf16 v[0:15], v[38:41], v[120:123], v[0:15]
	global_load_dwordx4 v[38:41], v[42:43], off offset:64
	s_waitcnt vmcnt(0)
	v_mfma_f32_32x32x16_bf16 v[0:15], v[38:41], v[116:119], v[0:15]
	global_load_dwordx4 v[38:41], v[42:43], off offset:96
	s_waitcnt vmcnt(0)
	v_mfma_f32_32x32x16_bf16 v[0:15], v[38:41], v[112:115], v[0:15]
	global_load_dwordx4 v[38:41], v[42:43], off offset:128
	s_waitcnt vmcnt(0)
	v_mfma_f32_32x32x16_bf16 v[0:15], v[38:41], v[108:111], v[0:15]
	global_load_dwordx4 v[38:41], v[42:43], off offset:160
	s_waitcnt vmcnt(0)
	v_mfma_f32_32x32x16_bf16 v[0:15], v[38:41], v[104:107], v[0:15]
	global_load_dwordx4 v[38:41], v[42:43], off offset:192
	s_waitcnt vmcnt(0)
	v_mfma_f32_32x32x16_bf16 v[0:15], v[38:41], v[96:99], v[0:15]
	global_load_dwordx4 v[38:41], v[42:43], off offset:224
	v_add_co_u32_e32 v42, vcc, s46, v36
	s_nop 1
	v_addc_co_u32_e32 v43, vcc, 0, v37, vcc
	s_waitcnt vmcnt(0)
	v_mfma_f32_32x32x16_bf16 v[0:15], v[38:41], v[100:103], v[0:15]
	global_load_dwordx4 v[38:41], v[42:43], off
	v_add_co_u32_e32 v226, vcc, s15, v36
	s_nop 1
	v_addc_co_u32_e32 v227, vcc, 0, v37, vcc
	s_waitcnt vmcnt(0)
	v_mfma_f32_32x32x16_bf16 v[48:63], v[38:41], v[32:35], 0
	global_load_dwordx4 v[38:41], v[42:43], off offset:32
	s_waitcnt vmcnt(0)
	v_mfma_f32_32x32x16_bf16 v[48:63], v[38:41], v[120:123], v[48:63]
	global_load_dwordx4 v[38:41], v[42:43], off offset:64
	s_waitcnt vmcnt(0)
	v_mfma_f32_32x32x16_bf16 v[48:63], v[38:41], v[116:119], v[48:63]
	global_load_dwordx4 v[38:41], v[42:43], off offset:96
	s_waitcnt vmcnt(0)
	v_mfma_f32_32x32x16_bf16 v[48:63], v[38:41], v[112:115], v[48:63]
	global_load_dwordx4 v[38:41], v[42:43], off offset:128
	s_waitcnt vmcnt(0)
	v_mfma_f32_32x32x16_bf16 v[48:63], v[38:41], v[108:111], v[48:63]
	global_load_dwordx4 v[38:41], v[42:43], off offset:160
	s_waitcnt vmcnt(0)
	v_mfma_f32_32x32x16_bf16 v[48:63], v[38:41], v[104:107], v[48:63]
	global_load_dwordx4 v[38:41], v[42:43], off offset:192
	s_waitcnt vmcnt(0)
	v_mfma_f32_32x32x16_bf16 v[48:63], v[38:41], v[96:99], v[48:63]
	global_load_dwordx4 v[38:41], v[42:43], off offset:224
	global_load_dwordx4 v[248:251], v[226:227], off offset:32
	s_waitcnt vmcnt(1)
	v_mfma_f32_32x32x16_bf16 v[48:63], v[38:41], v[100:103], v[48:63]
	global_load_dwordx4 v[36:39], v[226:227], off
	s_waitcnt vmcnt(0)
; #define GAS __attribute__((address_space(1)))
; __device__ __forceinline__ unsigned short f2bf(float f) { return (unsigned short)(pk2(f, 0.f) & 0xffffu); }
; __device__ __forceinline__ void fft_phase(const Params& p, LAS unsigned char* lds, int tid) {
;     ...
;                 for (int s = 0; s < 8; ++s) {
;                     const bf16x8 a = *(const GAS bf16x8*)(fap + mt * 32 * 128 + 16 * s);
;                     acc[mt] = __builtin_amdgcn_mfma_f32_32x32x16_bf16(a, bfA[s], acc[mt], 0, 0, 0);
;                 }
;                 asm volatile("" ::: "memory");
;             }
; #pragma unroll
;             for (int rg = 0; rg < 4; ++rg) { tw0[1][rg] = *(const GAS f32x4*)(twp + (32 + 8 * rg) * 2); tw1[1][rg] = *(const GAS f32x4*)(twp + (32 + 8 * rg) * 2 + 4); }
; #pragma unroll
;             for (int mt = 0; mt < 2; ++mt)
; #pragma unroll
;                 for (int rg = 0; rg < 4; ++rg) {
;                     const int k1b = 32 * mt + 8 * rg + 4 * hi;
;                     const f32x4 t0 = tw0[mt][rg], t1 = tw1[mt][rg];
;                     const float ct[4] = {t0[0], t0[2], t1[0], t1[2]}, st[4] = {t0[1], t0[3], t1[1], t1[3]};
; #pragma unroll
;                     for (int e = 0; e < 4; ++e) {
;                         const int k1 = k1b + e; const float tr = acc[mt][4 * rg + e], ti = acc[mt + 2][4 * rg + e];
;                         const int pos = k1 * 64 + ((((n2 >> 3) ^ (k1 & 3)) << 3) | (n2 & 7));
;                         Zr[pos] = f2bf(tr * ct[e] + ti * st[e]); Zi[pos] = f2bf(ti * ct[e] - tr * st[e]);
;                     }
;                 }
	v_mfma_f32_32x32x16_bf16 v[32:47], v[36:39], v[32:35], 0
	v_mfma_f32_32x32x16_bf16 v[32:47], v[248:251], v[120:123], v[32:47]
	global_load_dwordx4 v[120:123], v[226:227], off offset:64
	s_waitcnt vmcnt(0)
	v_mfma_f32_32x32x16_bf16 v[32:47], v[120:123], v[116:119], v[32:47]
	global_load_dwordx4 v[116:119], v[226:227], off offset:96
	s_waitcnt vmcnt(0)
	v_mfma_f32_32x32x16_bf16 v[32:47], v[116:119], v[112:115], v[32:47]
	global_load_dwordx4 v[112:115], v[226:227], off offset:128
	s_waitcnt vmcnt(0)
	v_mfma_f32_32x32x16_bf16 v[32:47], v[112:115], v[108:111], v[32:47]
	global_load_dwordx4 v[108:111], v[226:227], off offset:160
	s_waitcnt vmcnt(0)
	v_mfma_f32_32x32x16_bf16 v[32:47], v[108:111], v[104:107], v[32:47]
	global_load_dwordx4 v[104:107], v[226:227], off offset:192
	s_waitcnt vmcnt(0)
	v_mfma_f32_32x32x16_bf16 v[32:47], v[104:107], v[96:99], v[32:47]
	global_load_dwordx4 v[96:99], v[226:227], off offset:224
	s_waitcnt vmcnt(0)
	v_mfma_f32_32x32x16_bf16 v[32:47], v[96:99], v[100:103], v[32:47]
	global_load_dwordx4 v[100:103], v[126:127], off offset:272
	global_load_dwordx4 v[104:107], v[126:127], off offset:256
	global_load_dwordx4 v[108:111], v[126:127], off offset:336
	global_load_dwordx4 v[112:115], v[126:127], off offset:320
	global_load_dwordx4 v[116:119], v[126:127], off offset:400
	global_load_dwordx4 v[120:123], v[126:127], off offset:384
	global_load_dwordx4 v[96:99], v[126:127], off offset:464
	global_load_dwordx4 v[248:251], v[126:127], off offset:448
	v_mul_f32_e32 v126, v93, v48
	v_fmac_f32_e32 v126, v92, v16
	v_mul_f32_e32 v16, v93, v16
	v_fma_f32 v16, v92, v48, -v16
	v_cvt_pk_bf16_f32 v16, v16, s0
	ds_write_b16 v133, v16
	v_mul_f32_e32 v16, v95, v49
	v_fmac_f32_e32 v16, v94, v17
	v_cvt_pk_bf16_f32 v126, v126, s0
	v_cvt_pk_bf16_f32 v16, v16, s0
	ds_write_b16 v132, v126
	ds_write_b16 v134, v16 offset:128
	v_mul_f32_e32 v16, v95, v17
	v_fma_f32 v16, v94, v49, -v16
	v_cvt_pk_bf16_f32 v16, v16, s0
	ds_write_b16 v135, v16
	v_mul_f32_e32 v16, v89, v50
	v_fmac_f32_e32 v16, v88, v18
	v_cvt_pk_bf16_f32 v16, v16, s0
	ds_write_b16 v136, v16 offset:256
	v_mul_f32_e32 v16, v89, v18
	v_fma_f32 v16, v88, v50, -v16
	v_cvt_pk_bf16_f32 v16, v16, s0
	ds_write_b16 v137, v16
	v_mul_f32_e32 v16, v91, v51
	v_fmac_f32_e32 v16, v90, v19
	v_cvt_pk_bf16_f32 v16, v16, s0
	ds_write_b16 v138, v16 offset:384
	v_mul_f32_e32 v16, v91, v19
	v_fma_f32 v16, v90, v51, -v16
	v_cvt_pk_bf16_f32 v16, v16, s0
	ds_write_b16 v139, v16
	v_mul_f32_e32 v16, v85, v52
	v_fmac_f32_e32 v16, v84, v20
	v_cvt_pk_bf16_f32 v16, v16, s0
	ds_write_b16 v132, v16 offset:1024
	v_mul_f32_e32 v16, v85, v20
	v_fma_f32 v16, v84, v52, -v16
	v_cvt_pk_bf16_f32 v16, v16, s0
	ds_write_b16 v140, v16
	v_mul_f32_e32 v16, v87, v53
	v_fmac_f32_e32 v16, v86, v21
	v_cvt_pk_bf16_f32 v16, v16, s0
	ds_write_b16 v134, v16 offset:1152
	v_mul_f32_e32 v16, v87, v21
	v_fma_f32 v16, v86, v53, -v16
	v_cvt_pk_bf16_f32 v16, v16, s0
	ds_write_b16 v141, v16
	v_mul_f32_e32 v16, v81, v54
	v_fmac_f32_e32 v16, v80, v22
	v_cvt_pk_bf16_f32 v16, v16, s0
	ds_write_b16 v136, v16 offset:1280
	v_mul_f32_e32 v16, v81, v22
	v_fma_f32 v16, v80, v54, -v16
	v_cvt_pk_bf16_f32 v16, v16, s0
	ds_write_b16 v142, v16
	v_mul_f32_e32 v16, v83, v55
	v_fmac_f32_e32 v16, v82, v23
	v_cvt_pk_bf16_f32 v16, v16, s0
	ds_write_b16 v138, v16 offset:1408
	v_mul_f32_e32 v16, v83, v23
	v_fma_f32 v16, v82, v55, -v16
	v_cvt_pk_bf16_f32 v16, v16, s0
	ds_write_b16 v143, v16
	v_mul_f32_e32 v16, v77, v56
	v_fmac_f32_e32 v16, v76, v24
	v_cvt_pk_bf16_f32 v16, v16, s0
	ds_write_b16 v132, v16 offset:2048
	v_mul_f32_e32 v16, v77, v24
	v_fma_f32 v16, v76, v56, -v16
	v_cvt_pk_bf16_f32 v16, v16, s0
	ds_write_b16 v145, v16
	v_mul_f32_e32 v16, v79, v57
	v_fmac_f32_e32 v16, v78, v25
	v_cvt_pk_bf16_f32 v16, v16, s0
	ds_write_b16 v134, v16 offset:2176
	v_mul_f32_e32 v16, v79, v25
	v_fma_f32 v16, v78, v57, -v16
	v_cvt_pk_bf16_f32 v16, v16, s0
	ds_write_b16 v146, v16
	v_mul_f32_e32 v16, v73, v58
	v_fmac_f32_e32 v16, v72, v26
	v_cvt_pk_bf16_f32 v16, v16, s0
	ds_write_b16 v136, v16 offset:2304
	v_mul_f32_e32 v16, v73, v26
	v_fma_f32 v16, v72, v58, -v16
	v_cvt_pk_bf16_f32 v16, v16, s0
	ds_write_b16 v147, v16
	v_mul_f32_e32 v16, v75, v59
	v_fmac_f32_e32 v16, v74, v27
	v_cvt_pk_bf16_f32 v16, v16, s0
	ds_write_b16 v138, v16 offset:2432
	v_mul_f32_e32 v16, v75, v27
	v_fma_f32 v16, v74, v59, -v16
	v_cvt_pk_bf16_f32 v16, v16, s0
	ds_write_b16 v148, v16
	v_mul_f32_e32 v16, v69, v60
	v_fmac_f32_e32 v16, v68, v28
	v_cvt_pk_bf16_f32 v16, v16, s0
	ds_write_b16 v132, v16 offset:3072
	v_mul_f32_e32 v16, v69, v28
	v_fma_f32 v16, v68, v60, -v16
	v_cvt_pk_bf16_f32 v16, v16, s0
	ds_write_b16 v149, v16
	v_mul_f32_e32 v16, v71, v61
	v_fmac_f32_e32 v16, v70, v29
	v_cvt_pk_bf16_f32 v16, v16, s0
	ds_write_b16 v134, v16 offset:3200
	v_mul_f32_e32 v16, v71, v29
	v_fma_f32 v16, v70, v61, -v16
	v_cvt_pk_bf16_f32 v16, v16, s0
	ds_write_b16 v150, v16
	v_mul_f32_e32 v16, v65, v62
	v_fmac_f32_e32 v16, v64, v30
	v_cvt_pk_bf16_f32 v16, v16, s0
	ds_write_b16 v136, v16 offset:3328
	v_mul_f32_e32 v16, v65, v30
	v_fma_f32 v16, v64, v62, -v16
	v_cvt_pk_bf16_f32 v16, v16, s0
	ds_write_b16 v151, v16
	v_mul_f32_e32 v16, v67, v63
	v_fmac_f32_e32 v16, v66, v31
	v_cvt_pk_bf16_f32 v16, v16, s0
	ds_write_b16 v138, v16 offset:3456
	v_mul_f32_e32 v16, v67, v31
	v_fma_f32 v16, v66, v63, -v16
	v_cvt_pk_bf16_f32 v16, v16, s0
	ds_write_b16 v152, v16
	s_waitcnt vmcnt(6)
; __device__ __forceinline__ void fft_phase(const Params& p, LAS unsigned char* lds, int tid) {
;     ...
;         for (int nh = 0; nh < 2; ++nh) {
;             const int n2 = nh * 32 + r32;
;             int two = (n2 * 64 + 4 * hi) * 2; asm volatile("" : "+v"(two));
;             const GAS float* twp = (const GAS float*)TW + two;
;             f32x4 tw0[2][4], tw1[2][4];
; #pragma unroll
;             for (int rg = 0; rg < 4; ++rg) { tw0[0][rg] = *(const GAS f32x4*)(twp + (8 * rg) * 2); tw1[0][rg] = *(const GAS f32x4*)(twp + (8 * rg) * 2 + 4); }
;             bf16x8 bfA[8];
; #pragma unroll
;             for (int s = 0; s < 8; ++s) {
;                 const LAS unsigned short* q = Z + ((s >> 2) * 8 + w) * 4096 + (16 * (s & 3) + 8 * hi) * 64 + n2;
;                 u32x4 t;
;                 t.x = (unsigned)q[0] | ((unsigned)q[64] << 16); t.y = (unsigned)q[128] | ((unsigned)q[192] << 16);
;                 t.z = (unsigned)q[256] | ((unsigned)q[320] << 16); t.w = (unsigned)q[384] | ((unsigned)q[448] << 16);
;                 bfA[s] = __builtin_bit_cast(bf16x8, t);
;             }
;             f32x16 acc[4];
;             int fao = r32 * 128 + 8 * hi; asm volatile("" : "+v"(fao));
;             const GAS bf16_t* fap = (const GAS bf16_t*)FA + fao;
; #pragma unroll
;             for (int mt = 0; mt < 4; ++mt) {
; #pragma unroll
;                 for (int e = 0; e < 16; ++e) acc[mt][e] = 0.f;
; #pragma unroll
;                 for (int s = 0; s < 8; ++s) {
;                     const bf16x8 a = *(const GAS bf16x8*)(fap + mt * 32 * 128 + 16 * s);
;                     acc[mt] = __builtin_amdgcn_mfma_f32_32x32x16_bf16(a, bfA[s], acc[mt], 0, 0, 0);
;                 }
;                 asm volatile("" ::: "memory");
;             }
; #pragma unroll
;             for (int rg = 0; rg < 4; ++rg) { tw0[1][rg] = *(const GAS f32x4*)(twp + (32 + 8 * rg) * 2); tw1[1][rg] = *(const GAS f32x4*)(twp + (32 + 8 * rg) * 2 + 4); }
; #pragma unroll
;             for (int mt = 0; mt < 2; ++mt)
; #pragma unroll
;                 for (int rg = 0; rg < 4; ++rg) {
;                     const int k1b = 32 * mt + 8 * rg + 4 * hi;
;                     const f32x4 t0 = tw0[mt][rg], t1 = tw1[mt][rg];
;                     const float ct[4] = {t0[0], t0[2], t1[0], t1[2]}, st[4] = {t0[1], t0[3], t1[1], t1[3]};
; #pragma unroll
;                     for (int e = 0; e < 4; ++e) {
	v_mul_f32_e32 v16, v32, v105
	v_fmac_f32_e32 v16, v0, v104
	v_mul_f32_e32 v0, v0, v105
	v_fma_f32 v0, v32, v104, -v0
	v_cvt_pk_bf16_f32 v0, v0, s0
	ds_write_b16 v153, v0
	v_mul_f32_e32 v0, v33, v107
	v_fmac_f32_e32 v0, v1, v106
	v_cvt_pk_bf16_f32 v16, v16, s0
	v_cvt_pk_bf16_f32 v0, v0, s0
	ds_write_b16 v132, v16 offset:4096
	ds_write_b16 v134, v0 offset:4224
	v_mul_f32_e32 v0, v1, v107
	v_fma_f32 v0, v33, v106, -v0
	v_cvt_pk_bf16_f32 v0, v0, s0
	ds_write_b16 v154, v0
	v_mul_f32_e32 v0, v34, v101
	v_fmac_f32_e32 v0, v2, v100
	v_cvt_pk_bf16_f32 v0, v0, s0
	ds_write_b16 v136, v0 offset:4352
	v_mul_f32_e32 v0, v2, v101
	v_fma_f32 v0, v34, v100, -v0
	v_cvt_pk_bf16_f32 v0, v0, s0
	ds_write_b16 v155, v0
	v_mul_f32_e32 v0, v35, v103
	v_fmac_f32_e32 v0, v3, v102
	v_cvt_pk_bf16_f32 v0, v0, s0
	ds_write_b16 v138, v0 offset:4480
	v_mul_f32_e32 v0, v3, v103
	v_fma_f32 v0, v35, v102, -v0
	v_cvt_pk_bf16_f32 v0, v0, s0
	ds_write_b16 v156, v0
	s_waitcnt vmcnt(4)
	v_mul_f32_e32 v0, v36, v113
	v_fmac_f32_e32 v0, v4, v112
	v_cvt_pk_bf16_f32 v0, v0, s0
	ds_write_b16 v132, v0 offset:5120
	v_mul_f32_e32 v0, v4, v113
	v_fma_f32 v0, v36, v112, -v0
	v_cvt_pk_bf16_f32 v0, v0, s0
	ds_write_b16 v157, v0
	v_mul_f32_e32 v0, v37, v115
	v_fmac_f32_e32 v0, v5, v114
	v_cvt_pk_bf16_f32 v0, v0, s0
	ds_write_b16 v134, v0 offset:5248
	v_mul_f32_e32 v0, v5, v115
	v_fma_f32 v0, v37, v114, -v0
	v_cvt_pk_bf16_f32 v0, v0, s0
	ds_write_b16 v158, v0
	v_mul_f32_e32 v0, v38, v109
	v_fmac_f32_e32 v0, v6, v108
	v_cvt_pk_bf16_f32 v0, v0, s0
	ds_write_b16 v136, v0 offset:5376
	v_mul_f32_e32 v0, v6, v109
	v_fma_f32 v0, v38, v108, -v0
	v_cvt_pk_bf16_f32 v0, v0, s0
	ds_write_b16 v159, v0
	v_mul_f32_e32 v0, v39, v111
	v_fmac_f32_e32 v0, v7, v110
	v_cvt_pk_bf16_f32 v0, v0, s0
	ds_write_b16 v138, v0 offset:5504
	v_mul_f32_e32 v0, v7, v111
	v_fma_f32 v0, v39, v110, -v0
	v_cvt_pk_bf16_f32 v0, v0, s0
	ds_write_b16 v160, v0
	s_waitcnt vmcnt(2)
	v_mul_f32_e32 v0, v40, v121
	v_fmac_f32_e32 v0, v8, v120
	v_cvt_pk_bf16_f32 v0, v0, s0
	ds_write_b16 v132, v0 offset:6144
	v_mul_f32_e32 v0, v8, v121
	v_fma_f32 v0, v40, v120, -v0
	v_cvt_pk_bf16_f32 v0, v0, s0
	ds_write_b16 v161, v0
	v_mul_f32_e32 v0, v41, v123
	v_fmac_f32_e32 v0, v9, v122
	v_cvt_pk_bf16_f32 v0, v0, s0
	ds_write_b16 v134, v0 offset:6272
	v_mul_f32_e32 v0, v9, v123
	v_fma_f32 v0, v41, v122, -v0
	v_cvt_pk_bf16_f32 v0, v0, s0
	ds_write_b16 v162, v0
	v_mul_f32_e32 v0, v42, v117
	v_fmac_f32_e32 v0, v10, v116
	v_cvt_pk_bf16_f32 v0, v0, s0
	ds_write_b16 v136, v0 offset:6400
	v_mul_f32_e32 v0, v10, v117
	v_fma_f32 v0, v42, v116, -v0
	v_cvt_pk_bf16_f32 v0, v0, s0
	ds_write_b16 v163, v0
	v_mul_f32_e32 v0, v43, v119
	v_fmac_f32_e32 v0, v11, v118
	v_cvt_pk_bf16_f32 v0, v0, s0
	ds_write_b16 v138, v0 offset:6528
	v_mul_f32_e32 v0, v11, v119
	v_fma_f32 v0, v43, v118, -v0
	v_cvt_pk_bf16_f32 v0, v0, s0
	ds_write_b16 v164, v0
	s_waitcnt vmcnt(0)
	v_mul_f32_e32 v0, v44, v249
	v_fmac_f32_e32 v0, v12, v248
	v_cvt_pk_bf16_f32 v0, v0, s0
	ds_write_b16 v132, v0 offset:7168
	v_mul_f32_e32 v0, v12, v249
	v_fma_f32 v0, v44, v248, -v0
	v_cvt_pk_bf16_f32 v0, v0, s0
	ds_write_b16 v165, v0
	v_mul_f32_e32 v0, v45, v251
	v_fmac_f32_e32 v0, v13, v250
	v_cvt_pk_bf16_f32 v0, v0, s0
	ds_write_b16 v134, v0 offset:7296
	v_mul_f32_e32 v0, v13, v251
	v_fma_f32 v0, v45, v250, -v0
	v_cvt_pk_bf16_f32 v0, v0, s0
	ds_write_b16 v166, v0
	v_mul_f32_e32 v0, v46, v97
	v_fmac_f32_e32 v0, v14, v96
	v_cvt_pk_bf16_f32 v0, v0, s0
	ds_write_b16 v136, v0 offset:7424
	v_mul_f32_e32 v0, v14, v97
	v_fma_f32 v0, v46, v96, -v0
	v_cvt_pk_bf16_f32 v0, v0, s0
	ds_write_b16 v167, v0
	v_mul_f32_e32 v0, v47, v99
	v_fmac_f32_e32 v0, v15, v98
	v_cvt_pk_bf16_f32 v0, v0, s0
	ds_write_b16 v138, v0 offset:7552
	v_mul_f32_e32 v0, v15, v99
	v_fma_f32 v0, v47, v98, -v0
	v_cvt_pk_bf16_f32 v0, v0, s0
	ds_write_b16 v168, v0
	v_mov_b32_e32 v0, v169
	s_nop 0
	v_ashrrev_i32_e32 v1, 31, v0
	v_lshl_add_u64 v[126:127], v[0:1], 2, s[12:13]
	global_load_dwordx4 v[88:91], v[126:127], off offset:16
	global_load_dwordx4 v[92:95], v[126:127], off
	global_load_dwordx4 v[80:83], v[126:127], off offset:80
	global_load_dwordx4 v[84:87], v[126:127], off offset:64
	global_load_dwordx4 v[72:75], v[126:127], off offset:144
	global_load_dwordx4 v[76:79], v[126:127], off offset:128
	global_load_dwordx4 v[64:67], v[126:127], off offset:208
	global_load_dwordx4 v[68:71], v[126:127], off offset:192
	ds_read_u16 v0, v130 offset:64
	ds_read_u16 v1, v130 offset:192
	ds_read_u16 v2, v130 offset:320
	ds_read_u16 v3, v130 offset:448
	ds_read_u16 v4, v130 offset:576
	ds_read_u16 v5, v130 offset:704
	ds_read_u16 v6, v130 offset:832
	ds_read_u16 v7, v130 offset:960
	ds_read_u16 v8, v130 offset:2112
	ds_read_u16 v9, v130 offset:2240
	ds_read_u16 v10, v130 offset:2368
	ds_read_u16 v11, v130 offset:2496
	ds_read_u16 v12, v130 offset:2624
	ds_read_u16 v13, v130 offset:2752
	ds_read_u16 v14, v130 offset:2880
	ds_read_u16 v15, v130 offset:3008
	s_waitcnt lgkmcnt(0)
	v_lshl_or_b32 v32, v1, 16, v0
	v_lshl_or_b32 v33, v3, 16, v2
	v_lshl_or_b32 v34, v5, 16, v4
	v_lshl_or_b32 v35, v7, 16, v6
	v_lshl_or_b32 v120, v9, 16, v8
	v_lshl_or_b32 v121, v11, 16, v10
	v_lshl_or_b32 v122, v13, 16, v12
	v_lshl_or_b32 v123, v15, 16, v14
	ds_read_u16 v0, v130 offset:4160
	ds_read_u16 v1, v130 offset:4288
	ds_read_u16 v2, v130 offset:4416
	ds_read_u16 v3, v130 offset:4544
	ds_read_u16 v4, v130 offset:4672
	ds_read_u16 v5, v130 offset:4800
	ds_read_u16 v6, v130 offset:4928
	ds_read_u16 v7, v130 offset:5056
	ds_read_u16 v8, v130 offset:6208
	ds_read_u16 v9, v130 offset:6336
	ds_read_u16 v10, v130 offset:6464
	ds_read_u16 v11, v130 offset:6592
	ds_read_u16 v12, v130 offset:6720
	ds_read_u16 v13, v130 offset:6848
	ds_read_u16 v14, v130 offset:6976
	ds_read_u16 v15, v130 offset:7104
	s_waitcnt lgkmcnt(0)
; #define LAS __attribute__((address_space(3)))
; #define GAS __attribute__((address_space(1)))
; __device__ __forceinline__ void fft_phase(const Params& p, LAS unsigned char* lds, int tid) {
;     ...
;             bf16x8 bfA[8];
; #pragma unroll
;             for (int s = 0; s < 8; ++s) {
;                 const LAS unsigned short* q = Z + ((s >> 2) * 8 + w) * 4096 + (16 * (s & 3) + 8 * hi) * 64 + n2;
;                 u32x4 t;
;                 t.x = (unsigned)q[0] | ((unsigned)q[64] << 16); t.y = (unsigned)q[128] | ((unsigned)q[192] << 16);
;                 t.z = (unsigned)q[256] | ((unsigned)q[320] << 16); t.w = (unsigned)q[384] | ((unsigned)q[448] << 16);
;                 bfA[s] = __builtin_bit_cast(bf16x8, t);
;             }
;             f32x16 acc[4];
;             int fao = r32 * 128 + 8 * hi; asm volatile("" : "+v"(fao));
;             const GAS bf16_t* fap = (const GAS bf16_t*)FA + fao;
; #pragma unroll
;             for (int mt = 0; mt < 4; ++mt) {
; #pragma unroll
;                 for (int e = 0; e < 16; ++e) acc[mt][e] = 0.f;
; #pragma unroll
;                 for (int s = 0; s < 8; ++s) {
;                     const bf16x8 a = *(const GAS bf16x8*)(fap + mt * 32 * 128 + 16 * s);
;                     acc[mt] = __builtin_amdgcn_mfma_f32_32x32x16_bf16(a, bfA[s], acc[mt], 0, 0, 0);
;                 }
;                 asm volatile("" ::: "memory");
;             }
	v_lshl_or_b32 v116, v1, 16, v0
	v_lshl_or_b32 v117, v3, 16, v2
	v_lshl_or_b32 v118, v5, 16, v4
	v_lshl_or_b32 v119, v7, 16, v6
	v_lshl_or_b32 v112, v9, 16, v8
	v_lshl_or_b32 v113, v11, 16, v10
	v_lshl_or_b32 v114, v13, 16, v12
	v_lshl_or_b32 v115, v15, 16, v14
	ds_read_u16 v0, v131 offset:64
	ds_read_u16 v1, v131 offset:192
	ds_read_u16 v2, v131 offset:320
	ds_read_u16 v3, v131 offset:448
	ds_read_u16 v4, v131 offset:576
	ds_read_u16 v5, v131 offset:704
	ds_read_u16 v6, v131 offset:832
	ds_read_u16 v7, v131 offset:960
	ds_read_u16 v8, v131 offset:2112
	ds_read_u16 v9, v131 offset:2240
	ds_read_u16 v10, v131 offset:2368
	ds_read_u16 v11, v131 offset:2496
	ds_read_u16 v12, v131 offset:2624
	ds_read_u16 v13, v131 offset:2752
	ds_read_u16 v14, v131 offset:2880
	ds_read_u16 v15, v131 offset:3008
	s_waitcnt lgkmcnt(0)
	v_lshl_or_b32 v108, v1, 16, v0
	v_lshl_or_b32 v109, v3, 16, v2
	v_lshl_or_b32 v110, v5, 16, v4
	v_lshl_or_b32 v111, v7, 16, v6
	v_lshl_or_b32 v104, v9, 16, v8
	v_lshl_or_b32 v105, v11, 16, v10
	v_lshl_or_b32 v106, v13, 16, v12
	v_lshl_or_b32 v107, v15, 16, v14
	ds_read_u16 v0, v131 offset:4160
	ds_read_u16 v1, v131 offset:4288
	ds_read_u16 v2, v131 offset:4416
	ds_read_u16 v3, v131 offset:4544
	ds_read_u16 v4, v131 offset:4672
	ds_read_u16 v5, v131 offset:4800
	ds_read_u16 v6, v131 offset:4928
	ds_read_u16 v7, v131 offset:5056
	ds_read_u16 v8, v131 offset:6208
	ds_read_u16 v9, v131 offset:6336
	ds_read_u16 v10, v131 offset:6464
	ds_read_u16 v11, v131 offset:6592
	ds_read_u16 v12, v131 offset:6720
	ds_read_u16 v13, v131 offset:6848
	ds_read_u16 v14, v131 offset:6976
	ds_read_u16 v15, v131 offset:7104
	s_waitcnt lgkmcnt(0)
	v_lshl_or_b32 v96, v1, 16, v0
	v_lshl_or_b32 v97, v3, 16, v2
	v_lshl_or_b32 v98, v5, 16, v4
	v_lshl_or_b32 v99, v7, 16, v6
	v_lshl_or_b32 v100, v9, 16, v8
	v_lshl_or_b32 v101, v11, 16, v10
	v_lshl_or_b32 v102, v13, 16, v12
	v_lshl_or_b32 v103, v15, 16, v14
	v_mov_b32_e32 v0, v129
	s_nop 0
	v_ashrrev_i32_e32 v1, 31, v0
	v_lshl_add_u64 v[36:37], v[0:1], 1, s[28:29]
	global_load_dwordx4 v[0:3], v[36:37], off
	s_waitcnt vmcnt(0)
	v_mfma_f32_32x32x16_bf16 v[16:31], v[0:3], v[32:35], 0
	global_load_dwordx4 v[0:3], v[36:37], off offset:32
	v_add_co_u32_e32 v42, vcc, s19, v36
	s_nop 1
	v_addc_co_u32_e32 v43, vcc, 0, v37, vcc
	s_waitcnt vmcnt(0)
	v_mfma_f32_32x32x16_bf16 v[16:31], v[0:3], v[120:123], v[16:31]
	global_load_dwordx4 v[0:3], v[36:37], off offset:64
	s_waitcnt vmcnt(0)
	v_mfma_f32_32x32x16_bf16 v[16:31], v[0:3], v[116:119], v[16:31]
	global_load_dwordx4 v[0:3], v[36:37], off offset:96
	s_waitcnt vmcnt(0)
	v_mfma_f32_32x32x16_bf16 v[16:31], v[0:3], v[112:115], v[16:31]
	global_load_dwordx4 v[0:3], v[36:37], off offset:128
	s_waitcnt vmcnt(0)
	v_mfma_f32_32x32x16_bf16 v[16:31], v[0:3], v[108:111], v[16:31]
	global_load_dwordx4 v[0:3], v[36:37], off offset:160
	s_waitcnt vmcnt(0)
	v_mfma_f32_32x32x16_bf16 v[16:31], v[0:3], v[104:107], v[16:31]
	global_load_dwordx4 v[0:3], v[36:37], off offset:192
	s_waitcnt vmcnt(0)
	v_mfma_f32_32x32x16_bf16 v[16:31], v[0:3], v[96:99], v[16:31]
	global_load_dwordx4 v[0:3], v[36:37], off offset:224
	global_load_dwordx4 v[38:41], v[42:43], off offset:32
	s_waitcnt vmcnt(1)
	v_mfma_f32_32x32x16_bf16 v[16:31], v[0:3], v[100:103], v[16:31]
	global_load_dwordx4 v[0:3], v[42:43], off
	s_waitcnt vmcnt(0)
	v_mfma_f32_32x32x16_bf16 v[0:15], v[0:3], v[32:35], 0
	v_mfma_f32_32x32x16_bf16 v[0:15], v[38:41], v[120:123], v[0:15]
	global_load_dwordx4 v[38:41], v[42:43], off offset:64
	s_waitcnt vmcnt(0)
	v_mfma_f32_32x32x16_bf16 v[0:15], v[38:41], v[116:119], v[0:15]
	global_load_dwordx4 v[38:41], v[42:43], off offset:96
	s_waitcnt vmcnt(0)
	v_mfma_f32_32x32x16_bf16 v[0:15], v[38:41], v[112:115], v[0:15]
	global_load_dwordx4 v[38:41], v[42:43], off offset:128
	s_waitcnt vmcnt(0)
	v_mfma_f32_32x32x16_bf16 v[0:15], v[38:41], v[108:111], v[0:15]
	global_load_dwordx4 v[38:41], v[42:43], off offset:160
	s_waitcnt vmcnt(0)
	v_mfma_f32_32x32x16_bf16 v[0:15], v[38:41], v[104:107], v[0:15]
	global_load_dwordx4 v[38:41], v[42:43], off offset:192
	s_waitcnt vmcnt(0)
	v_mfma_f32_32x32x16_bf16 v[0:15], v[38:41], v[96:99], v[0:15]
	global_load_dwordx4 v[38:41], v[42:43], off offset:224
	v_add_co_u32_e32 v42, vcc, s46, v36
	s_nop 1
	v_addc_co_u32_e32 v43, vcc, 0, v37, vcc
	s_waitcnt vmcnt(0)
	v_mfma_f32_32x32x16_bf16 v[0:15], v[38:41], v[100:103], v[0:15]
	global_load_dwordx4 v[38:41], v[42:43], off
	v_add_co_u32_e32 v226, vcc, s15, v36
	s_nop 1
	v_addc_co_u32_e32 v227, vcc, 0, v37, vcc
	s_waitcnt vmcnt(0)
	v_mfma_f32_32x32x16_bf16 v[48:63], v[38:41], v[32:35], 0
	global_load_dwordx4 v[38:41], v[42:43], off offset:32
	s_waitcnt vmcnt(0)
	v_mfma_f32_32x32x16_bf16 v[48:63], v[38:41], v[120:123], v[48:63]
	global_load_dwordx4 v[38:41], v[42:43], off offset:64
	s_waitcnt vmcnt(0)
	v_mfma_f32_32x32x16_bf16 v[48:63], v[38:41], v[116:119], v[48:63]
	global_load_dwordx4 v[38:41], v[42:43], off offset:96
	s_waitcnt vmcnt(0)
	v_mfma_f32_32x32x16_bf16 v[48:63], v[38:41], v[112:115], v[48:63]
	global_load_dwordx4 v[38:41], v[42:43], off offset:128
	s_waitcnt vmcnt(0)
	v_mfma_f32_32x32x16_bf16 v[48:63], v[38:41], v[108:111], v[48:63]
	global_load_dwordx4 v[38:41], v[42:43], off offset:160
	s_waitcnt vmcnt(0)
	v_mfma_f32_32x32x16_bf16 v[48:63], v[38:41], v[104:107], v[48:63]
	global_load_dwordx4 v[38:41], v[42:43], off offset:192
	s_waitcnt vmcnt(0)
	v_mfma_f32_32x32x16_bf16 v[48:63], v[38:41], v[96:99], v[48:63]
	global_load_dwordx4 v[38:41], v[42:43], off offset:224
	global_load_dwordx4 v[248:251], v[226:227], off offset:32
	s_waitcnt vmcnt(1)
	v_mfma_f32_32x32x16_bf16 v[48:63], v[38:41], v[100:103], v[48:63]
	global_load_dwordx4 v[36:39], v[226:227], off
	s_waitcnt vmcnt(0)
; #define GAS __attribute__((address_space(1)))
; __device__ __forceinline__ unsigned short f2bf(float f) { return (unsigned short)(pk2(f, 0.f) & 0xffffu); }
; __device__ __forceinline__ void fft_phase(const Params& p, LAS unsigned char* lds, int tid) {
;     ...
;                 for (int s = 0; s < 8; ++s) {
;                     const bf16x8 a = *(const GAS bf16x8*)(fap + mt * 32 * 128 + 16 * s);
;                     acc[mt] = __builtin_amdgcn_mfma_f32_32x32x16_bf16(a, bfA[s], acc[mt], 0, 0, 0);
;                 }
;                 asm volatile("" ::: "memory");
;             }
; #pragma unroll
;             for (int rg = 0; rg < 4; ++rg) { tw0[1][rg] = *(const GAS f32x4*)(twp + (32 + 8 * rg) * 2); tw1[1][rg] = *(const GAS f32x4*)(twp + (32 + 8 * rg) * 2 + 4); }
; #pragma unroll
;             for (int mt = 0; mt < 2; ++mt)
; #pragma unroll
;                 for (int rg = 0; rg < 4; ++rg) {
;                     const int k1b = 32 * mt + 8 * rg + 4 * hi;
;                     const f32x4 t0 = tw0[mt][rg], t1 = tw1[mt][rg];
;                     const float ct[4] = {t0[0], t0[2], t1[0], t1[2]}, st[4] = {t0[1], t0[3], t1[1], t1[3]};
; #pragma unroll
;                     for (int e = 0; e < 4; ++e) {
;                         const int k1 = k1b + e; const float tr = acc[mt][4 * rg + e], ti = acc[mt + 2][4 * rg + e];
;                         const int pos = k1 * 64 + ((((n2 >> 3) ^ (k1 & 3)) << 3) | (n2 & 7));
;                         Zr[pos] = f2bf(tr * ct[e] + ti * st[e]); Zi[pos] = f2bf(ti * ct[e] - tr * st[e]);
;                     }
;                 }
	v_mfma_f32_32x32x16_bf16 v[32:47], v[36:39], v[32:35], 0
	v_mfma_f32_32x32x16_bf16 v[32:47], v[248:251], v[120:123], v[32:47]
	global_load_dwordx4 v[120:123], v[226:227], off offset:64
	s_waitcnt vmcnt(0)
	v_mfma_f32_32x32x16_bf16 v[32:47], v[120:123], v[116:119], v[32:47]
	global_load_dwordx4 v[116:119], v[226:227], off offset:96
	s_waitcnt vmcnt(0)
	v_mfma_f32_32x32x16_bf16 v[32:47], v[116:119], v[112:115], v[32:47]
	global_load_dwordx4 v[112:115], v[226:227], off offset:128
	s_waitcnt vmcnt(0)
	v_mfma_f32_32x32x16_bf16 v[32:47], v[112:115], v[108:111], v[32:47]
	global_load_dwordx4 v[108:111], v[226:227], off offset:160
	s_waitcnt vmcnt(0)
	v_mfma_f32_32x32x16_bf16 v[32:47], v[108:111], v[104:107], v[32:47]
	global_load_dwordx4 v[104:107], v[226:227], off offset:192
	s_waitcnt vmcnt(0)
	v_mfma_f32_32x32x16_bf16 v[32:47], v[104:107], v[96:99], v[32:47]
	global_load_dwordx4 v[96:99], v[226:227], off offset:224
	s_waitcnt vmcnt(0)
	v_mfma_f32_32x32x16_bf16 v[32:47], v[96:99], v[100:103], v[32:47]
	global_load_dwordx4 v[100:103], v[126:127], off offset:272
	global_load_dwordx4 v[104:107], v[126:127], off offset:256
	global_load_dwordx4 v[108:111], v[126:127], off offset:336
	global_load_dwordx4 v[112:115], v[126:127], off offset:320
	global_load_dwordx4 v[116:119], v[126:127], off offset:400
	global_load_dwordx4 v[120:123], v[126:127], off offset:384
	global_load_dwordx4 v[96:99], v[126:127], off offset:464
	global_load_dwordx4 v[248:251], v[126:127], off offset:448
	v_mul_f32_e32 v126, v93, v48
	v_fmac_f32_e32 v126, v92, v16
	v_mul_f32_e32 v16, v93, v16
	v_fma_f32 v16, v92, v48, -v16
	v_cvt_pk_bf16_f32 v16, v16, s0
	ds_write_b16 v171, v16
	v_mul_f32_e32 v16, v95, v49
	v_fmac_f32_e32 v16, v94, v17
	v_cvt_pk_bf16_f32 v126, v126, s0
	v_cvt_pk_bf16_f32 v16, v16, s0
	ds_write_b16 v170, v126
	ds_write_b16 v172, v16 offset:128
	v_mul_f32_e32 v16, v95, v17
	v_fma_f32 v16, v94, v49, -v16
	v_cvt_pk_bf16_f32 v16, v16, s0
	ds_write_b16 v173, v16
	v_mul_f32_e32 v16, v89, v50
	v_fmac_f32_e32 v16, v88, v18
	v_cvt_pk_bf16_f32 v16, v16, s0
	ds_write_b16 v174, v16 offset:256
	v_mul_f32_e32 v16, v89, v18
	v_fma_f32 v16, v88, v50, -v16
	v_cvt_pk_bf16_f32 v16, v16, s0
	ds_write_b16 v175, v16
	v_mul_f32_e32 v16, v91, v51
	v_fmac_f32_e32 v16, v90, v19
	v_cvt_pk_bf16_f32 v16, v16, s0
	ds_write_b16 v176, v16 offset:384
	v_mul_f32_e32 v16, v91, v19
	v_fma_f32 v16, v90, v51, -v16
	v_cvt_pk_bf16_f32 v16, v16, s0
	ds_write_b16 v177, v16
	v_mul_f32_e32 v16, v85, v52
	v_fmac_f32_e32 v16, v84, v20
	v_cvt_pk_bf16_f32 v16, v16, s0
	ds_write_b16 v170, v16 offset:1024
	v_mul_f32_e32 v16, v85, v20
	v_fma_f32 v16, v84, v52, -v16
	v_cvt_pk_bf16_f32 v16, v16, s0
	ds_write_b16 v178, v16
	v_mul_f32_e32 v16, v87, v53
	v_fmac_f32_e32 v16, v86, v21
	v_cvt_pk_bf16_f32 v16, v16, s0
	ds_write_b16 v172, v16 offset:1152
	v_mul_f32_e32 v16, v87, v21
	v_fma_f32 v16, v86, v53, -v16
	v_cvt_pk_bf16_f32 v16, v16, s0
	ds_write_b16 v179, v16
	v_mul_f32_e32 v16, v81, v54
	v_fmac_f32_e32 v16, v80, v22
	v_cvt_pk_bf16_f32 v16, v16, s0
	ds_write_b16 v174, v16 offset:1280
	v_mul_f32_e32 v16, v81, v22
	v_fma_f32 v16, v80, v54, -v16
	v_cvt_pk_bf16_f32 v16, v16, s0
	ds_write_b16 v180, v16
	v_mul_f32_e32 v16, v83, v55
	v_fmac_f32_e32 v16, v82, v23
	v_cvt_pk_bf16_f32 v16, v16, s0
	ds_write_b16 v176, v16 offset:1408
	v_mul_f32_e32 v16, v83, v23
	v_fma_f32 v16, v82, v55, -v16
	v_cvt_pk_bf16_f32 v16, v16, s0
	ds_write_b16 v181, v16
	v_mul_f32_e32 v16, v77, v56
	v_fmac_f32_e32 v16, v76, v24
	v_cvt_pk_bf16_f32 v16, v16, s0
	ds_write_b16 v170, v16 offset:2048
	v_mul_f32_e32 v16, v77, v24
	v_fma_f32 v16, v76, v56, -v16
	v_cvt_pk_bf16_f32 v16, v16, s0
	ds_write_b16 v182, v16
	v_mul_f32_e32 v16, v79, v57
	v_fmac_f32_e32 v16, v78, v25
	v_cvt_pk_bf16_f32 v16, v16, s0
	ds_write_b16 v172, v16 offset:2176
	v_mul_f32_e32 v16, v79, v25
	v_fma_f32 v16, v78, v57, -v16
	v_cvt_pk_bf16_f32 v16, v16, s0
	ds_write_b16 v183, v16
	v_mul_f32_e32 v16, v73, v58
	v_fmac_f32_e32 v16, v72, v26
	v_cvt_pk_bf16_f32 v16, v16, s0
	ds_write_b16 v174, v16 offset:2304
	v_mul_f32_e32 v16, v73, v26
	v_fma_f32 v16, v72, v58, -v16
	v_cvt_pk_bf16_f32 v16, v16, s0
	ds_write_b16 v184, v16
	v_mul_f32_e32 v16, v75, v59
	v_fmac_f32_e32 v16, v74, v27
	v_cvt_pk_bf16_f32 v16, v16, s0
	ds_write_b16 v176, v16 offset:2432
	v_mul_f32_e32 v16, v75, v27
	v_fma_f32 v16, v74, v59, -v16
	v_cvt_pk_bf16_f32 v16, v16, s0
	ds_write_b16 v185, v16
	v_mul_f32_e32 v16, v69, v60
	v_fmac_f32_e32 v16, v68, v28
	v_cvt_pk_bf16_f32 v16, v16, s0
	ds_write_b16 v170, v16 offset:3072
	v_mul_f32_e32 v16, v69, v28
	v_fma_f32 v16, v68, v60, -v16
	v_cvt_pk_bf16_f32 v16, v16, s0
	ds_write_b16 v186, v16
	v_mul_f32_e32 v16, v71, v61
	v_fmac_f32_e32 v16, v70, v29
	v_cvt_pk_bf16_f32 v16, v16, s0
	ds_write_b16 v172, v16 offset:3200
	v_mul_f32_e32 v16, v71, v29
	v_fma_f32 v16, v70, v61, -v16
	v_cvt_pk_bf16_f32 v16, v16, s0
	ds_write_b16 v192, v16
	v_mul_f32_e32 v16, v65, v62
	v_fmac_f32_e32 v16, v64, v30
	v_cvt_pk_bf16_f32 v16, v16, s0
	ds_write_b16 v174, v16 offset:3328
	v_mul_f32_e32 v16, v65, v30
	v_fma_f32 v16, v64, v62, -v16
	v_cvt_pk_bf16_f32 v16, v16, s0
	ds_write_b16 v193, v16
	v_mul_f32_e32 v16, v67, v63
	v_fmac_f32_e32 v16, v66, v31
	v_cvt_pk_bf16_f32 v16, v16, s0
	ds_write_b16 v176, v16 offset:3456
	v_mul_f32_e32 v16, v67, v31
	v_fma_f32 v16, v66, v63, -v16
	v_cvt_pk_bf16_f32 v16, v16, s0
	ds_write_b16 v194, v16
	s_waitcnt vmcnt(6)
; #define LAS __attribute__((address_space(3)))
; #define GAS __attribute__((address_space(1)))
; __device__ __forceinline__ unsigned short f2bf(float f) { return (unsigned short)(pk2(f, 0.f) & 0xffffu); }
; __device__ __forceinline__ void fft_phase(const Params& p, LAS unsigned char* lds, int tid) {
;     ...
;                     const float ct[4] = {t0[0], t0[2], t1[0], t1[2]}, st[4] = {t0[1], t0[3], t1[1], t1[3]};
; #pragma unroll
;                     for (int e = 0; e < 4; ++e) {
;                         const int k1 = k1b + e; const float tr = acc[mt][4 * rg + e], ti = acc[mt + 2][4 * rg + e];
;                         const int pos = k1 * 64 + ((((n2 >> 3) ^ (k1 & 3)) << 3) | (n2 & 7));
;                         Zr[pos] = f2bf(tr * ct[e] + ti * st[e]); Zi[pos] = f2bf(ti * ct[e] - tr * st[e]);
;                     }
;                 }
;         }
;         __syncthreads();
;         f32x16 y[2][2];
; #pragma unroll
;         for (int nt = 0; nt < 2; ++nt) {
;             const int k1 = nt * 32 + r32;
;             bf16x8 bfB[8];
; #pragma unroll
;             for (int s = 0; s < 8; ++s) bfB[s] = *(const LAS bf16x8*)(Z + ((s >> 2) * 8 + w) * 4096 + k1 * 64 + (((2 * (s & 3) + hi) ^ (k1 & 3)) << 3));
;             int fbo = r32 * 128 + 8 * hi; asm volatile("" : "+v"(fbo));
;             const GAS bf16_t* fbp = (const GAS bf16_t*)FB + fbo;
; #pragma unroll
;             for (int mt = 0; mt < 2; ++mt) {
; #pragma unroll
;                 for (int e = 0; e < 16; ++e) y[mt][nt][e] = 0.f;
; #pragma unroll
;                 for (int s = 0; s < 8; ++s) {
;                     const bf16x8 a = *(const GAS bf16x8*)(fbp + mt * 32 * 128 + 16 * s);
;                     y[mt][nt] = __builtin_amdgcn_mfma_f32_32x32x16_bf16(a, bfB[s], y[mt][nt], 0, 0, 0);
;                 }
;                 asm volatile("" ::: "memory");
;             }
	v_mul_f32_e32 v16, v32, v105
	v_fmac_f32_e32 v16, v0, v104
	v_mul_f32_e32 v0, v0, v105
	v_fma_f32 v0, v32, v104, -v0
	v_cvt_pk_bf16_f32 v0, v0, s0
	ds_write_b16 v195, v0
	v_mul_f32_e32 v0, v33, v107
	v_fmac_f32_e32 v0, v1, v106
	v_cvt_pk_bf16_f32 v16, v16, s0
	v_cvt_pk_bf16_f32 v0, v0, s0
	ds_write_b16 v170, v16 offset:4096
	ds_write_b16 v172, v0 offset:4224
	v_mul_f32_e32 v0, v1, v107
	v_fma_f32 v0, v33, v106, -v0
	v_cvt_pk_bf16_f32 v0, v0, s0
	ds_write_b16 v196, v0
	v_mul_f32_e32 v0, v34, v101
	v_fmac_f32_e32 v0, v2, v100
	v_cvt_pk_bf16_f32 v0, v0, s0
	ds_write_b16 v174, v0 offset:4352
	v_mul_f32_e32 v0, v2, v101
	v_fma_f32 v0, v34, v100, -v0
	v_cvt_pk_bf16_f32 v0, v0, s0
	ds_write_b16 v197, v0
	v_mul_f32_e32 v0, v35, v103
	v_fmac_f32_e32 v0, v3, v102
	v_cvt_pk_bf16_f32 v0, v0, s0
	ds_write_b16 v176, v0 offset:4480
	v_mul_f32_e32 v0, v3, v103
	v_fma_f32 v0, v35, v102, -v0
	v_cvt_pk_bf16_f32 v0, v0, s0
	ds_write_b16 v198, v0
	s_waitcnt vmcnt(4)
	v_mul_f32_e32 v0, v36, v113
	v_fmac_f32_e32 v0, v4, v112
	v_cvt_pk_bf16_f32 v0, v0, s0
	ds_write_b16 v170, v0 offset:5120
	v_mul_f32_e32 v0, v4, v113
	v_fma_f32 v0, v36, v112, -v0
	v_cvt_pk_bf16_f32 v0, v0, s0
	ds_write_b16 v199, v0
	v_mul_f32_e32 v0, v37, v115
	v_fmac_f32_e32 v0, v5, v114
	v_cvt_pk_bf16_f32 v0, v0, s0
	ds_write_b16 v172, v0 offset:5248
	v_mul_f32_e32 v0, v5, v115
	v_fma_f32 v0, v37, v114, -v0
	v_cvt_pk_bf16_f32 v0, v0, s0
	ds_write_b16 v200, v0
	v_mul_f32_e32 v0, v38, v109
	v_fmac_f32_e32 v0, v6, v108
	v_cvt_pk_bf16_f32 v0, v0, s0
	ds_write_b16 v174, v0 offset:5376
	v_mul_f32_e32 v0, v6, v109
	v_fma_f32 v0, v38, v108, -v0
	v_cvt_pk_bf16_f32 v0, v0, s0
	ds_write_b16 v201, v0
	v_mul_f32_e32 v0, v39, v111
	v_fmac_f32_e32 v0, v7, v110
	v_cvt_pk_bf16_f32 v0, v0, s0
	ds_write_b16 v176, v0 offset:5504
	v_mul_f32_e32 v0, v7, v111
	v_fma_f32 v0, v39, v110, -v0
	v_cvt_pk_bf16_f32 v0, v0, s0
	ds_write_b16 v202, v0
	s_waitcnt vmcnt(2)
	v_mul_f32_e32 v0, v40, v121
	v_fmac_f32_e32 v0, v8, v120
	v_cvt_pk_bf16_f32 v0, v0, s0
	ds_write_b16 v170, v0 offset:6144
	v_mul_f32_e32 v0, v8, v121
	v_fma_f32 v0, v40, v120, -v0
	v_cvt_pk_bf16_f32 v0, v0, s0
	ds_write_b16 v203, v0
	v_mul_f32_e32 v0, v41, v123
	v_fmac_f32_e32 v0, v9, v122
	v_cvt_pk_bf16_f32 v0, v0, s0
	ds_write_b16 v172, v0 offset:6272
	v_mul_f32_e32 v0, v9, v123
	v_fma_f32 v0, v41, v122, -v0
	v_cvt_pk_bf16_f32 v0, v0, s0
	ds_write_b16 v204, v0
	v_mul_f32_e32 v0, v42, v117
	v_fmac_f32_e32 v0, v10, v116
	v_cvt_pk_bf16_f32 v0, v0, s0
	ds_write_b16 v174, v0 offset:6400
	v_mul_f32_e32 v0, v10, v117
	v_fma_f32 v0, v42, v116, -v0
	v_cvt_pk_bf16_f32 v0, v0, s0
	ds_write_b16 v205, v0
	v_mul_f32_e32 v0, v43, v119
	v_fmac_f32_e32 v0, v11, v118
	v_cvt_pk_bf16_f32 v0, v0, s0
	ds_write_b16 v176, v0 offset:6528
	v_mul_f32_e32 v0, v11, v119
	v_fma_f32 v0, v43, v118, -v0
	v_cvt_pk_bf16_f32 v0, v0, s0
	ds_write_b16 v206, v0
	s_waitcnt vmcnt(0)
	v_mul_f32_e32 v0, v44, v249
	v_fmac_f32_e32 v0, v12, v248
	v_cvt_pk_bf16_f32 v0, v0, s0
	ds_write_b16 v170, v0 offset:7168
	v_mul_f32_e32 v0, v12, v249
	v_fma_f32 v0, v44, v248, -v0
	v_cvt_pk_bf16_f32 v0, v0, s0
	ds_write_b16 v207, v0
	v_mul_f32_e32 v0, v45, v251
	v_fmac_f32_e32 v0, v13, v250
	v_cvt_pk_bf16_f32 v0, v0, s0
	ds_write_b16 v172, v0 offset:7296
	v_mul_f32_e32 v0, v13, v251
	v_fma_f32 v0, v45, v250, -v0
	v_cvt_pk_bf16_f32 v0, v0, s0
	ds_write_b16 v208, v0
	v_mul_f32_e32 v0, v46, v97
	v_fmac_f32_e32 v0, v14, v96
	v_cvt_pk_bf16_f32 v0, v0, s0
	ds_write_b16 v174, v0 offset:7424
	v_mul_f32_e32 v0, v14, v97
	v_fma_f32 v0, v46, v96, -v0
	v_cvt_pk_bf16_f32 v0, v0, s0
	ds_write_b16 v209, v0
	v_mul_f32_e32 v0, v47, v99
	v_fmac_f32_e32 v0, v15, v98
	v_cvt_pk_bf16_f32 v0, v0, s0
	ds_write_b16 v176, v0 offset:7552
	v_mul_f32_e32 v0, v15, v99
	v_fma_f32 v0, v47, v98, -v0
	v_cvt_pk_bf16_f32 v0, v0, s0
	v_add_u32_e32 v66, v211, v212
	v_add_u32_e32 v4, v216, v212
	ds_write_b16 v210, v0
	s_waitcnt lgkmcnt(0)
	s_barrier
	ds_read_b128 v[0:3], v66
	ds_read_b128 v[44:47], v4
	v_add_u32_e32 v67, v211, v213
	v_add_u32_e32 v4, v216, v213
	ds_read_b128 v[32:35], v67
	ds_read_b128 v[48:51], v4
	v_add_u32_e32 v68, v211, v214
	v_add_u32_e32 v4, v216, v214
	ds_read_b128 v[36:39], v68
	ds_read_b128 v[52:55], v4
	v_add_u32_e32 v76, v211, v215
	v_add_u32_e32 v4, v216, v215
	ds_read_b128 v[40:43], v76
	ds_read_b128 v[56:59], v4
	v_mov_b32_e32 v4, v129
	s_nop 0
	v_ashrrev_i32_e32 v5, 31, v4
	v_lshl_add_u64 v[8:9], v[4:5], 1, s[42:43]
	global_load_dwordx4 v[4:7], v[8:9], off
	s_waitcnt vmcnt(0) lgkmcnt(7)
	v_mfma_f32_32x32x16_bf16 v[16:31], v[4:7], v[0:3], 0
	global_load_dwordx4 v[4:7], v[8:9], off offset:32
	v_add_co_u32_e32 v64, vcc, s19, v8
	s_nop 1
	v_addc_co_u32_e32 v65, vcc, 0, v9, vcc
	s_waitcnt vmcnt(0) lgkmcnt(5)
	v_mfma_f32_32x32x16_bf16 v[16:31], v[4:7], v[32:35], v[16:31]
	global_load_dwordx4 v[4:7], v[8:9], off offset:64
	s_waitcnt vmcnt(0) lgkmcnt(3)
	v_mfma_f32_32x32x16_bf16 v[16:31], v[4:7], v[36:39], v[16:31]
	global_load_dwordx4 v[4:7], v[8:9], off offset:96
	s_waitcnt vmcnt(0) lgkmcnt(1)
	v_mfma_f32_32x32x16_bf16 v[16:31], v[4:7], v[40:43], v[16:31]
	global_load_dwordx4 v[4:7], v[8:9], off offset:128
	s_waitcnt vmcnt(0)
	v_mfma_f32_32x32x16_bf16 v[16:31], v[4:7], v[44:47], v[16:31]
	global_load_dwordx4 v[4:7], v[8:9], off offset:160
	s_waitcnt vmcnt(0)
	v_mfma_f32_32x32x16_bf16 v[16:31], v[4:7], v[48:51], v[16:31]
	global_load_dwordx4 v[4:7], v[8:9], off offset:192
	s_waitcnt vmcnt(0)
	v_mfma_f32_32x32x16_bf16 v[16:31], v[4:7], v[52:55], v[16:31]
	global_load_dwordx4 v[4:7], v[8:9], off offset:224
	global_load_dwordx4 v[60:63], v[64:65], off offset:32
	s_waitcnt vmcnt(1) lgkmcnt(0)
; #define LAS __attribute__((address_space(3)))
; #define GAS __attribute__((address_space(1)))
; __device__ __forceinline__ unsigned short f2bf(float f) { return (unsigned short)(pk2(f, 0.f) & 0xffffu); }
; __device__ __forceinline__ void fft_phase(const Params& p, LAS unsigned char* lds, int tid) {
;     ...
;         f32x16 y[2][2];
; #pragma unroll
;         for (int nt = 0; nt < 2; ++nt) {
;             const int k1 = nt * 32 + r32;
;             bf16x8 bfB[8];
; #pragma unroll
;             for (int s = 0; s < 8; ++s) bfB[s] = *(const LAS bf16x8*)(Z + ((s >> 2) * 8 + w) * 4096 + k1 * 64 + (((2 * (s & 3) + hi) ^ (k1 & 3)) << 3));
;             int fbo = r32 * 128 + 8 * hi; asm volatile("" : "+v"(fbo));
;             const GAS bf16_t* fbp = (const GAS bf16_t*)FB + fbo;
; #pragma unroll
;             for (int mt = 0; mt < 2; ++mt) {
; #pragma unroll
;                 for (int e = 0; e < 16; ++e) y[mt][nt][e] = 0.f;
; #pragma unroll
;                 for (int s = 0; s < 8; ++s) {
;                     const bf16x8 a = *(const GAS bf16x8*)(fbp + mt * 32 * 128 + 16 * s);
;                     y[mt][nt] = __builtin_amdgcn_mfma_f32_32x32x16_bf16(a, bfB[s], y[mt][nt], 0, 0, 0);
;                 }
;                 asm volatile("" ::: "memory");
;             }
;         }
;         __syncthreads();
; #pragma unroll
;         for (int mt = 0; mt < 2; ++mt)
; #pragma unroll
;             for (int nt = 0; nt < 2; ++nt)
; #pragma unroll
;                 for (int e = 0; e < 16; ++e) {
;                     const int k2 = 32 * mt + (e & 3) + 8 * (e >> 2) + 4 * hi, k = nt * 32 + r32 + 64 * k2;
;                     Z[k * 8 + w] = f2bf(y[mt][nt][e]);
;                 }
	v_mfma_f32_32x32x16_bf16 v[16:31], v[4:7], v[56:59], v[16:31]
	global_load_dwordx4 v[4:7], v[64:65], off
	s_nop 10
	v_cvt_pk_bf16_f32 v16, v16, s0
	s_waitcnt vmcnt(0)
	v_mfma_f32_32x32x16_bf16 v[0:15], v[4:7], v[0:3], 0
	v_mfma_f32_32x32x16_bf16 v[0:15], v[60:63], v[32:35], v[0:15]
	global_load_dwordx4 v[32:35], v[64:65], off offset:64
	s_waitcnt vmcnt(0)
	v_mfma_f32_32x32x16_bf16 v[0:15], v[32:35], v[36:39], v[0:15]
	global_load_dwordx4 v[32:35], v[64:65], off offset:96
	s_waitcnt vmcnt(0)
	v_mfma_f32_32x32x16_bf16 v[0:15], v[32:35], v[40:43], v[0:15]
	global_load_dwordx4 v[32:35], v[64:65], off offset:128
	s_waitcnt vmcnt(0)
	v_mfma_f32_32x32x16_bf16 v[0:15], v[32:35], v[44:47], v[0:15]
	global_load_dwordx4 v[32:35], v[64:65], off offset:160
	s_waitcnt vmcnt(0)
	v_mfma_f32_32x32x16_bf16 v[0:15], v[32:35], v[48:51], v[0:15]
	global_load_dwordx4 v[32:35], v[64:65], off offset:192
	s_waitcnt vmcnt(0)
	v_mfma_f32_32x32x16_bf16 v[0:15], v[32:35], v[52:55], v[0:15]
	global_load_dwordx4 v[32:35], v[64:65], off offset:224
	ds_read_b128 v[48:51], v66 offset:4096
	ds_read_b128 v[72:75], v67 offset:4096
	ds_read_b128 v[68:71], v68 offset:4096
	ds_read_b128 v[64:67], v76 offset:4096
	s_waitcnt vmcnt(0)
	v_mfma_f32_32x32x16_bf16 v[0:15], v[32:35], v[56:59], v[0:15]
	v_add_u32_e32 v32, v217, v212
	ds_read_b128 v[76:79], v32
	v_add_u32_e32 v32, v217, v213
	ds_read_b128 v[80:83], v32
	v_add_u32_e32 v32, v217, v214
	ds_read_b128 v[84:87], v32
	v_add_u32_e32 v32, v217, v215
	ds_read_b128 v[88:91], v32
	v_mov_b32_e32 v32, v129
	s_nop 2
	v_cvt_pk_bf16_f32 v0, v0, s0
	v_ashrrev_i32_e32 v33, 31, v32
	v_lshl_add_u64 v[56:57], v[32:33], 1, s[42:43]
	global_load_dwordx4 v[32:35], v[56:57], off
	global_load_dwordx4 v[52:55], v[56:57], off offset:32
	s_waitcnt vmcnt(1) lgkmcnt(7)
	v_mfma_f32_32x32x16_bf16 v[32:47], v[32:35], v[48:51], 0
	v_add_co_u32_e32 v96, vcc, s19, v56
	s_nop 1
	v_addc_co_u32_e32 v97, vcc, 0, v57, vcc
	s_waitcnt vmcnt(0) lgkmcnt(6)
	v_mfma_f32_32x32x16_bf16 v[32:47], v[52:55], v[72:75], v[32:47]
	global_load_dwordx4 v[52:55], v[56:57], off offset:64
	s_waitcnt vmcnt(0) lgkmcnt(5)
	v_mfma_f32_32x32x16_bf16 v[32:47], v[52:55], v[68:71], v[32:47]
	global_load_dwordx4 v[52:55], v[56:57], off offset:96
	s_waitcnt vmcnt(0) lgkmcnt(4)
	v_mfma_f32_32x32x16_bf16 v[32:47], v[52:55], v[64:67], v[32:47]
	global_load_dwordx4 v[52:55], v[56:57], off offset:128
	s_waitcnt vmcnt(0) lgkmcnt(3)
	v_mfma_f32_32x32x16_bf16 v[32:47], v[52:55], v[76:79], v[32:47]
	global_load_dwordx4 v[52:55], v[56:57], off offset:160
	s_waitcnt vmcnt(0) lgkmcnt(2)
	v_mfma_f32_32x32x16_bf16 v[32:47], v[52:55], v[80:83], v[32:47]
	global_load_dwordx4 v[52:55], v[56:57], off offset:192
	s_waitcnt vmcnt(0) lgkmcnt(1)
	v_mfma_f32_32x32x16_bf16 v[32:47], v[52:55], v[84:87], v[32:47]
	global_load_dwordx4 v[52:55], v[56:57], off offset:224
	global_load_dwordx4 v[92:95], v[96:97], off offset:32
	s_waitcnt vmcnt(1) lgkmcnt(0)
	v_mfma_f32_32x32x16_bf16 v[32:47], v[52:55], v[88:91], v[32:47]
	global_load_dwordx4 v[52:55], v[96:97], off
	s_waitcnt vmcnt(0)
	v_mfma_f32_32x32x16_bf16 v[48:63], v[52:55], v[48:51], 0
	v_mfma_f32_32x32x16_bf16 v[48:63], v[92:95], v[72:75], v[48:63]
	global_load_dwordx4 v[72:75], v[96:97], off offset:64
	s_waitcnt vmcnt(0)
	v_mfma_f32_32x32x16_bf16 v[48:63], v[72:75], v[68:71], v[48:63]
	global_load_dwordx4 v[68:71], v[96:97], off offset:96
	s_waitcnt vmcnt(0)
	v_mfma_f32_32x32x16_bf16 v[48:63], v[68:71], v[64:67], v[48:63]
	global_load_dwordx4 v[64:67], v[96:97], off offset:128
	s_waitcnt vmcnt(0)
	v_mfma_f32_32x32x16_bf16 v[48:63], v[64:67], v[76:79], v[48:63]
	global_load_dwordx4 v[64:67], v[96:97], off offset:160
	s_waitcnt vmcnt(0)
	v_mfma_f32_32x32x16_bf16 v[48:63], v[64:67], v[80:83], v[48:63]
	global_load_dwordx4 v[64:67], v[96:97], off offset:192
	s_waitcnt vmcnt(0)
	v_mfma_f32_32x32x16_bf16 v[48:63], v[64:67], v[84:87], v[48:63]
	global_load_dwordx4 v[64:67], v[96:97], off offset:224
	s_barrier
	ds_write_b16 v218, v16
	v_cvt_pk_bf16_f32 v16, v17, s0
	ds_write_b16 v218, v0 offset:32768
	v_cvt_pk_bf16_f32 v0, v1, s0
	ds_write_b16 v218, v16 offset:1024
	v_cvt_pk_bf16_f32 v16, v18, s0
	ds_write_b16 v218, v0 offset:33792
	v_cvt_pk_bf16_f32 v0, v2, s0
	ds_write_b16 v218, v16 offset:2048
	v_cvt_pk_bf16_f32 v16, v19, s0
	ds_write_b16 v218, v0 offset:34816
	v_cvt_pk_bf16_f32 v0, v3, s0
	ds_write_b16 v218, v16 offset:3072
	v_cvt_pk_bf16_f32 v16, v20, s0
	ds_write_b16 v218, v0 offset:35840
	v_cvt_pk_bf16_f32 v0, v4, s0
	ds_write_b16 v218, v16 offset:8192
	v_cvt_pk_bf16_f32 v16, v21, s0
	ds_write_b16 v218, v0 offset:40960
	v_cvt_pk_bf16_f32 v0, v5, s0
	ds_write_b16 v218, v16 offset:9216
	v_cvt_pk_bf16_f32 v16, v22, s0
	ds_write_b16 v218, v0 offset:41984
	v_cvt_pk_bf16_f32 v0, v6, s0
	ds_write_b16 v218, v16 offset:10240
	v_cvt_pk_bf16_f32 v16, v23, s0
	ds_write_b16 v218, v0 offset:43008
	v_cvt_pk_bf16_f32 v0, v7, s0
	s_waitcnt vmcnt(0)
; #define LAS __attribute__((address_space(3)))
; __device__ __forceinline__ unsigned short f2bf(float f) { return (unsigned short)(pk2(f, 0.f) & 0xffffu); }
; __device__ __forceinline__ void fft_phase(const Params& p, LAS unsigned char* lds, int tid) {
;     ...
; #pragma unroll
;         for (int mt = 0; mt < 2; ++mt)
; #pragma unroll
;             for (int nt = 0; nt < 2; ++nt)
; #pragma unroll
;                 for (int e = 0; e < 16; ++e) {
;                     const int k2 = 32 * mt + (e & 3) + 8 * (e >> 2) + 4 * hi, k = nt * 32 + r32 + 64 * k2;
;                     Z[k * 8 + w] = f2bf(y[mt][nt][e]);
;                 }
;         __syncthreads();
; #pragma unroll
;         for (int j = 0; j < 8; ++j) {
;             const int k = j * NTHREADS + tid;
;             const u32x4 v = *(const LAS u32x4*)(Z + k * 8);
;             bf16_t* d = MIX + (size_t)(b * SEQ + k) * KOUT + 512 + g * 64 + cb * 8;
;             *(u32x4*)d = v;
;         }
;         asm volatile("s_waitcnt lgkmcnt(0)" ::: "memory"); __builtin_amdgcn_s_barrier(); asm volatile("" ::: "memory");
;     }
; }
	v_mfma_f32_32x32x16_bf16 v[48:63], v[64:67], v[88:91], v[48:63]
	ds_write_b16 v218, v16 offset:11264
	v_cvt_pk_bf16_f32 v16, v24, s0
	ds_write_b16 v218, v0 offset:44032
	v_cvt_pk_bf16_f32 v0, v8, s0
	ds_write_b16 v218, v16 offset:16384
	v_cvt_pk_bf16_f32 v16, v25, s0
	ds_write_b16 v218, v0 offset:49152
	v_cvt_pk_bf16_f32 v0, v9, s0
	ds_write_b16 v218, v16 offset:17408
	v_cvt_pk_bf16_f32 v16, v26, s0
	ds_write_b16 v218, v0 offset:50176
	v_cvt_pk_bf16_f32 v0, v10, s0
	ds_write_b16 v218, v16 offset:18432
	v_cvt_pk_bf16_f32 v16, v27, s0
	ds_write_b16 v218, v0 offset:51200
	v_cvt_pk_bf16_f32 v0, v11, s0
	ds_write_b16 v218, v16 offset:19456
	v_cvt_pk_bf16_f32 v16, v28, s0
	ds_write_b16 v218, v0 offset:52224
	v_cvt_pk_bf16_f32 v0, v12, s0
	ds_write_b16 v218, v16 offset:24576
	v_cvt_pk_bf16_f32 v16, v29, s0
	ds_write_b16 v218, v0 offset:57344
	v_cvt_pk_bf16_f32 v0, v13, s0
	ds_write_b16 v218, v16 offset:25600
	v_cvt_pk_bf16_f32 v16, v30, s0
	ds_write_b16 v218, v0 offset:58368
	v_cvt_pk_bf16_f32 v0, v14, s0
	ds_write_b16 v218, v16 offset:26624
	v_cvt_pk_bf16_f32 v16, v31, s0
	ds_write_b16 v218, v0 offset:59392
	v_cvt_pk_bf16_f32 v0, v15, s0
	ds_write_b16 v218, v16 offset:27648
	v_cvt_pk_bf16_f32 v16, v32, s0
	ds_write_b16 v218, v0 offset:60416
	v_cvt_pk_bf16_f32 v0, v48, s0
	ds_write_b16 v218, v16 offset:512
	v_cvt_pk_bf16_f32 v16, v33, s0
	ds_write_b16 v218, v0 offset:33280
	v_cvt_pk_bf16_f32 v0, v49, s0
	ds_write_b16 v218, v16 offset:1536
	v_cvt_pk_bf16_f32 v16, v34, s0
	ds_write_b16 v218, v0 offset:34304
	v_cvt_pk_bf16_f32 v0, v50, s0
	ds_write_b16 v218, v16 offset:2560
	v_cvt_pk_bf16_f32 v16, v35, s0
	ds_write_b16 v218, v0 offset:35328
	v_cvt_pk_bf16_f32 v0, v51, s0
	ds_write_b16 v218, v16 offset:3584
	v_cvt_pk_bf16_f32 v16, v36, s0
	ds_write_b16 v218, v0 offset:36352
	v_cvt_pk_bf16_f32 v0, v52, s0
	ds_write_b16 v218, v16 offset:8704
	v_cvt_pk_bf16_f32 v16, v37, s0
	ds_write_b16 v218, v0 offset:41472
	v_cvt_pk_bf16_f32 v0, v53, s0
	ds_write_b16 v218, v16 offset:9728
	v_cvt_pk_bf16_f32 v16, v38, s0
	ds_write_b16 v218, v0 offset:42496
	v_cvt_pk_bf16_f32 v0, v54, s0
	ds_write_b16 v218, v16 offset:10752
	v_cvt_pk_bf16_f32 v16, v39, s0
	ds_write_b16 v218, v0 offset:43520
	v_cvt_pk_bf16_f32 v0, v55, s0
	ds_write_b16 v218, v16 offset:11776
	v_cvt_pk_bf16_f32 v16, v40, s0
	ds_write_b16 v218, v0 offset:44544
	v_cvt_pk_bf16_f32 v0, v56, s0
	ds_write_b16 v218, v16 offset:16896
	v_cvt_pk_bf16_f32 v16, v41, s0
	ds_write_b16 v218, v0 offset:49664
	v_cvt_pk_bf16_f32 v0, v57, s0
	ds_write_b16 v218, v16 offset:17920
	v_cvt_pk_bf16_f32 v16, v42, s0
	ds_write_b16 v218, v0 offset:50688
	v_cvt_pk_bf16_f32 v0, v58, s0
	ds_write_b16 v218, v16 offset:18944
	v_cvt_pk_bf16_f32 v16, v43, s0
	ds_write_b16 v218, v0 offset:51712
	v_cvt_pk_bf16_f32 v0, v59, s0
	ds_write_b16 v218, v16 offset:19968
	v_cvt_pk_bf16_f32 v16, v44, s0
	ds_write_b16 v218, v0 offset:52736
	v_cvt_pk_bf16_f32 v0, v60, s0
	ds_write_b16 v218, v16 offset:25088
	v_cvt_pk_bf16_f32 v16, v45, s0
	ds_write_b16 v218, v0 offset:57856
	v_cvt_pk_bf16_f32 v0, v61, s0
	v_add_u32_e32 v4, s6, v144
	ds_write_b16 v218, v16 offset:26112
	v_cvt_pk_bf16_f32 v16, v46, s0
	ds_write_b16 v218, v0 offset:58880
	v_cvt_pk_bf16_f32 v0, v62, s0
	v_ashrrev_i32_e32 v5, 31, v4
	ds_write_b16 v218, v16 offset:27136
	v_cvt_pk_bf16_f32 v16, v47, s0
	ds_write_b16 v218, v0 offset:59904
	v_cvt_pk_bf16_f32 v0, v63, s0
	v_lshlrev_b64 v[4:5], 11, v[4:5]
	ds_write_b16 v218, v16 offset:28160
	ds_write_b16 v218, v0 offset:60928
	s_waitcnt lgkmcnt(0)
	s_barrier
	ds_read_b128 v[0:3], v128
	v_lshl_add_u64 v[4:5], s[88:89], 0, v[4:5]
	v_lshl_add_u64 v[4:5], v[4:5], 0, s[76:77]
	s_lshl_b32 s0, s0, 1
	v_lshl_add_u64 v[4:5], v[4:5], 0, s[0:1]
	v_add_co_u32_e32 v4, vcc, s22, v4
	s_cmpk_lt_i32 s5, 0x100
	s_nop 0
	v_addc_co_u32_e32 v5, vcc, 0, v5, vcc
	s_waitcnt lgkmcnt(0)
	global_store_dwordx4 v[4:5], v[0:3], off offset:1024
	v_add_u32_e32 v4, s6, v219
	v_ashrrev_i32_e32 v5, 31, v4
	v_lshlrev_b64 v[4:5], 11, v[4:5]
	ds_read_b128 v[0:3], v240
	v_lshl_add_u64 v[4:5], s[88:89], 0, v[4:5]
	v_lshl_add_u64 v[4:5], v[4:5], 0, s[76:77]
	v_lshl_add_u64 v[4:5], v[4:5], 0, s[0:1]
	v_add_co_u32_e32 v4, vcc, s22, v4
	s_nop 1
	v_addc_co_u32_e32 v5, vcc, 0, v5, vcc
	s_waitcnt lgkmcnt(0)
	global_store_dwordx4 v[4:5], v[0:3], off offset:1024
	v_add_u32_e32 v4, s6, v234
	v_ashrrev_i32_e32 v5, 31, v4
	v_lshlrev_b64 v[4:5], 11, v[4:5]
	ds_read_b128 v[0:3], v241
	v_lshl_add_u64 v[4:5], s[88:89], 0, v[4:5]
	v_lshl_add_u64 v[4:5], v[4:5], 0, s[76:77]
	v_lshl_add_u64 v[4:5], v[4:5], 0, s[0:1]
	v_add_co_u32_e32 v4, vcc, s22, v4
	s_nop 1
	v_addc_co_u32_e32 v5, vcc, 0, v5, vcc
	s_waitcnt lgkmcnt(0)
	global_store_dwordx4 v[4:5], v[0:3], off offset:1024
	v_add_u32_e32 v4, s6, v235
	v_ashrrev_i32_e32 v5, 31, v4
	v_lshlrev_b64 v[4:5], 11, v[4:5]
	ds_read_b128 v[0:3], v242
	v_lshl_add_u64 v[4:5], s[88:89], 0, v[4:5]
	v_lshl_add_u64 v[4:5], v[4:5], 0, s[76:77]
	v_lshl_add_u64 v[4:5], v[4:5], 0, s[0:1]
	v_add_co_u32_e32 v4, vcc, s22, v4
	s_nop 1
	v_addc_co_u32_e32 v5, vcc, 0, v5, vcc
	s_waitcnt lgkmcnt(0)
	global_store_dwordx4 v[4:5], v[0:3], off offset:1024
	v_add_u32_e32 v4, s6, v236
	v_ashrrev_i32_e32 v5, 31, v4
	v_lshlrev_b64 v[4:5], 11, v[4:5]
	ds_read_b128 v[0:3], v243
	v_lshl_add_u64 v[4:5], s[88:89], 0, v[4:5]
	v_lshl_add_u64 v[4:5], v[4:5], 0, s[76:77]
	v_lshl_add_u64 v[4:5], v[4:5], 0, s[0:1]
	v_add_co_u32_e32 v4, vcc, s22, v4
	s_nop 1
	v_addc_co_u32_e32 v5, vcc, 0, v5, vcc
	s_waitcnt lgkmcnt(0)
	global_store_dwordx4 v[4:5], v[0:3], off offset:1024
	v_add_u32_e32 v4, s6, v237
	v_ashrrev_i32_e32 v5, 31, v4
	v_lshlrev_b64 v[4:5], 11, v[4:5]
	ds_read_b128 v[0:3], v244
	v_lshl_add_u64 v[4:5], s[88:89], 0, v[4:5]
	v_lshl_add_u64 v[4:5], v[4:5], 0, s[76:77]
	v_lshl_add_u64 v[4:5], v[4:5], 0, s[0:1]
	v_add_co_u32_e32 v4, vcc, s22, v4
	s_nop 1
	v_addc_co_u32_e32 v5, vcc, 0, v5, vcc
	s_waitcnt lgkmcnt(0)
	global_store_dwordx4 v[4:5], v[0:3], off offset:1024
	v_add_u32_e32 v4, s6, v238
	v_ashrrev_i32_e32 v5, 31, v4
	v_lshlrev_b64 v[4:5], 11, v[4:5]
	ds_read_b128 v[0:3], v245
	v_lshl_add_u64 v[4:5], s[88:89], 0, v[4:5]
	v_lshl_add_u64 v[4:5], v[4:5], 0, s[76:77]
	v_lshl_add_u64 v[4:5], v[4:5], 0, s[0:1]
	v_add_co_u32_e32 v4, vcc, s22, v4
	s_nop 1
	v_addc_co_u32_e32 v5, vcc, 0, v5, vcc
	s_waitcnt lgkmcnt(0)
	global_store_dwordx4 v[4:5], v[0:3], off offset:1024
	v_add_u32_e32 v4, s6, v239
	v_ashrrev_i32_e32 v5, 31, v4
	v_lshlrev_b64 v[4:5], 11, v[4:5]
	ds_read_b128 v[0:3], v246
	v_lshl_add_u64 v[4:5], s[88:89], 0, v[4:5]
	v_lshl_add_u64 v[4:5], v[4:5], 0, s[76:77]
	v_lshl_add_u64 v[4:5], v[4:5], 0, s[0:1]
	v_add_co_u32_e32 v4, vcc, 0x18d00000, v4
	s_nop 1
	v_addc_co_u32_e32 v5, vcc, 0, v5, vcc
	s_waitcnt lgkmcnt(0)
	global_store_dwordx4 v[4:5], v[0:3], off offset:1024
	s_waitcnt lgkmcnt(0)
	s_barrier
	s_cbranch_scc1 .LBB0_454
